# lever 9 loop-edge edit: PEER token loops branch on SCC directly instead of cselect + s_and vcc + vccnz
# speedup vs baseline: 1.0019x; 1.0019x over previous
; DI float bflo(u32 u) { return __uint_as_float(u << 16); }
; DI float bfhi(u32 u) { return __uint_as_float(u & 0xffff0000u); }
; DI void dn2_math(const u32x4 (&W)[16], u32x4 x0, u32x4 x1, float* __restrict__ parow, int lane) {
;   f2 xf[8];
; #pragma unroll
;   for (int q = 0; q < 4; ++q) { xf[q] = f2{bflo(x0[q]), bfhi(x0[q])}; xf[4 + q] = f2{bflo(x1[q]), bfhi(x1[q])}; }
;   float pv[16];
; #pragma unroll
;   for (int j = 0; j < 16; ++j) {
;     f2 s2 = {0.f, 0.f};
; #pragma unroll
;     for (int d = 0; d < 4; ++d) {
;       f2 lo = __builtin_amdgcn_cvt_pk_f32_fp8((int)W[j][d], false);
;       f2 hi = __builtin_amdgcn_cvt_pk_f32_fp8((int)W[j][d], true);
;       s2 = lo * xf[2 * d] + s2;
;       s2 = hi * xf[2 * d + 1] + s2;
;     }
;     pv[j] = s2.x + s2.y;
;   }
; DI void peer_down2_phase(const Params& p, unsigned char* smem, int layer, const bf16* __restrict__ x1b, u32* ctr) {
;     ...
;       for (int tl = 0; tl < 16; tl += 2) {
;         dn2_issue(WB, pl + (tl + 1) * 128, wbase, grp);
;         xb_0 = *(const u32x4*)(xb0 + (size_t)(tl + 1) * 1024); xb_1 = *(const u32x4*)(xb0 + (size_t)(tl + 1) * 1024 + 8);
.LBB0_694:
	ds_read2_b32 v[134:135], v165 offset1:8
	ds_read2_b32 v[126:127], v165 offset0:16 offset1:24
	ds_read2_b32 v[118:119], v165 offset0:32 offset1:40
	ds_read2_b32 v[110:111], v165 offset0:48 offset1:56
	ds_read2_b32 v[102:103], v165 offset0:64 offset1:72
	ds_read2_b32 v[94:95], v165 offset0:80 offset1:88
	ds_read2_b32 v[86:87], v165 offset0:96 offset1:104
	ds_read2_b32 v[78:79], v165 offset0:112 offset1:120
	s_waitcnt lgkmcnt(7)
	v_lshl_add_u32 v130, v135, 10, v250
	v_lshl_add_u32 v134, v134, 10, v250
	global_load_dwordx4 v[134:137], v134, s[98:99]
	global_load_dwordx4 v[130:133], v130, s[98:99]
	s_waitcnt lgkmcnt(6)
	v_lshl_add_u32 v122, v127, 10, v250
	v_lshl_add_u32 v126, v126, 10, v250
	global_load_dwordx4 v[126:129], v126, s[98:99]
	global_load_dwordx4 v[122:125], v122, s[98:99]
	s_waitcnt lgkmcnt(5)
	v_lshl_add_u32 v114, v119, 10, v250
	v_lshl_add_u32 v118, v118, 10, v250
	global_load_dwordx4 v[118:121], v118, s[98:99]
	global_load_dwordx4 v[114:117], v114, s[98:99]
	s_waitcnt lgkmcnt(4)
	v_lshl_add_u32 v106, v111, 10, v250
	v_lshl_add_u32 v110, v110, 10, v250
	global_load_dwordx4 v[110:113], v110, s[98:99]
	global_load_dwordx4 v[106:109], v106, s[98:99]
	s_waitcnt lgkmcnt(3)
	v_lshl_add_u32 v98, v103, 10, v250
	v_lshl_add_u32 v102, v102, 10, v250
	global_load_dwordx4 v[102:105], v102, s[98:99]
	global_load_dwordx4 v[98:101], v98, s[98:99]
	s_waitcnt lgkmcnt(2)
	v_lshl_add_u32 v90, v95, 10, v250
	v_lshl_add_u32 v94, v94, 10, v250
	global_load_dwordx4 v[94:97], v94, s[98:99]
	global_load_dwordx4 v[90:93], v90, s[98:99]
	s_waitcnt lgkmcnt(1)
	v_lshl_add_u32 v82, v87, 10, v250
	v_lshl_add_u32 v86, v86, 10, v250
	global_load_dwordx4 v[86:89], v86, s[98:99]
	global_load_dwordx4 v[82:85], v82, s[98:99]
	s_waitcnt lgkmcnt(0)
	v_lshl_add_u32 v74, v79, 10, v250
	v_lshl_add_u32 v78, v78, 10, v250
	global_load_dwordx4 v[78:81], v78, s[98:99]
	global_load_dwordx4 v[74:77], v74, s[98:99]
	s_nop 0
	global_load_dwordx4 v[138:141], v[198:199], off offset:-2032
	global_load_dwordx4 v[142:145], v[198:199], off offset:-2048
	s_waitcnt vmcnt(35)
	v_cvt_pk_f32_fp8_e32 v[230:231], v2
	v_cvt_pk_f32_fp8_sdwa v[232:233], v2 src0_sel:WORD_1
	v_cvt_pk_f32_fp8_e32 v[234:235], v3
	s_waitcnt vmcnt(18)
	v_lshlrev_b32_e32 v210, 16, v70
	v_and_b32_e32 v211, 0xffff0000, v70
	v_cvt_pk_f32_fp8_sdwa v[236:237], v3 src0_sel:WORD_1
	v_lshlrev_b32_e32 v212, 16, v71
	v_and_b32_e32 v213, 0xffff0000, v71
	v_pk_fma_f32 v[230:231], v[230:231], v[210:211], 0 op_sel_hi:[1,1,0]
	v_lshlrev_b32_e32 v214, 16, v72
	v_and_b32_e32 v215, 0xffff0000, v72
	v_pk_fma_f32 v[230:231], v[232:233], v[212:213], v[230:231]
	v_cvt_pk_f32_fp8_e32 v[232:233], v4
	v_lshlrev_b32_e32 v216, 16, v73
	v_and_b32_e32 v217, 0xffff0000, v73
	v_pk_fma_f32 v[230:231], v[234:235], v[214:215], v[230:231]
	v_cvt_pk_f32_fp8_sdwa v[234:235], v4 src0_sel:WORD_1
	v_pk_fma_f32 v[230:231], v[236:237], v[216:217], v[230:231]
	v_cvt_pk_f32_fp8_e32 v[236:237], v5
	v_lshlrev_b32_e32 v202, 16, v66
	v_and_b32_e32 v203, 0xffff0000, v66
	v_cvt_pk_f32_fp8_sdwa v[238:239], v5 src0_sel:WORD_1
	v_lshlrev_b32_e32 v204, 16, v67
	v_and_b32_e32 v205, 0xffff0000, v67
	v_pk_fma_f32 v[230:231], v[232:233], v[202:203], v[230:231]
	v_lshlrev_b32_e32 v206, 16, v68
	v_and_b32_e32 v207, 0xffff0000, v68
	v_pk_fma_f32 v[230:231], v[234:235], v[204:205], v[230:231]
	v_lshlrev_b32_e32 v208, 16, v69
	v_and_b32_e32 v209, 0xffff0000, v69
	v_pk_fma_f32 v[230:231], v[236:237], v[206:207], v[230:231]
	v_cvt_pk_f32_fp8_sdwa v[232:233], v6 src0_sel:WORD_1
	v_pk_fma_f32 v[230:231], v[238:239], v[208:209], v[230:231]
	v_cvt_pk_f32_fp8_e32 v[234:235], v7
	v_add_f32_e32 v167, v230, v231
	v_cvt_pk_f32_fp8_e32 v[230:231], v6
	v_cvt_pk_f32_fp8_sdwa v[236:237], v7 src0_sel:WORD_1
	v_cvt_pk_f32_fp8_sdwa v[238:239], v9 src0_sel:WORD_1
	v_pk_fma_f32 v[230:231], v[230:231], v[210:211], 0 op_sel_hi:[1,1,0]
	s_nop 0
	v_pk_fma_f32 v[230:231], v[232:233], v[212:213], v[230:231]
	v_cvt_pk_f32_fp8_e32 v[232:233], v8
	v_pk_fma_f32 v[230:231], v[234:235], v[214:215], v[230:231]
	v_cvt_pk_f32_fp8_sdwa v[234:235], v8 src0_sel:WORD_1
	v_pk_fma_f32 v[230:231], v[236:237], v[216:217], v[230:231]
	v_cvt_pk_f32_fp8_e32 v[236:237], v9
	v_pk_fma_f32 v[230:231], v[232:233], v[202:203], v[230:231]
	v_cvt_pk_f32_fp8_sdwa v[232:233], v10 src0_sel:WORD_1
	v_pk_fma_f32 v[230:231], v[234:235], v[204:205], v[230:231]
	v_cvt_pk_f32_fp8_e32 v[234:235], v11
	v_pk_fma_f32 v[230:231], v[236:237], v[206:207], v[230:231]
	v_cvt_pk_f32_fp8_sdwa v[236:237], v11 src0_sel:WORD_1
	v_pk_fma_f32 v[230:231], v[238:239], v[208:209], v[230:231]
	v_cvt_pk_f32_fp8_sdwa v[238:239], v13 src0_sel:WORD_1
	v_add_f32_e32 v169, v230, v231
	v_cvt_pk_f32_fp8_e32 v[230:231], v10
	v_pk_fma_f32 v[230:231], v[230:231], v[210:211], 0 op_sel_hi:[1,1,0]
	s_nop 0
	v_pk_fma_f32 v[230:231], v[232:233], v[212:213], v[230:231]
	v_cvt_pk_f32_fp8_e32 v[232:233], v12
	v_pk_fma_f32 v[230:231], v[234:235], v[214:215], v[230:231]
	v_cvt_pk_f32_fp8_sdwa v[234:235], v12 src0_sel:WORD_1
	v_pk_fma_f32 v[230:231], v[236:237], v[216:217], v[230:231]
	v_cvt_pk_f32_fp8_e32 v[236:237], v13
	v_pk_fma_f32 v[230:231], v[232:233], v[202:203], v[230:231]
	v_cvt_pk_f32_fp8_sdwa v[232:233], v14 src0_sel:WORD_1
	v_pk_fma_f32 v[230:231], v[234:235], v[204:205], v[230:231]
	v_cvt_pk_f32_fp8_e32 v[234:235], v15
	v_pk_fma_f32 v[230:231], v[236:237], v[206:207], v[230:231]
	v_cvt_pk_f32_fp8_sdwa v[236:237], v15 src0_sel:WORD_1
	v_pk_fma_f32 v[230:231], v[238:239], v[208:209], v[230:231]
	v_cvt_pk_f32_fp8_sdwa v[238:239], v17 src0_sel:WORD_1
	v_add_f32_e32 v171, v230, v231
	v_cvt_pk_f32_fp8_e32 v[230:231], v14
	v_pk_fma_f32 v[230:231], v[230:231], v[210:211], 0 op_sel_hi:[1,1,0]
; DI void dn2_math(const u32x4 (&W)[16], u32x4 x0, u32x4 x1, float* __restrict__ parow, int lane) {
;     ...
; #pragma unroll
;   for (int j = 0; j < 16; ++j) {
;     f2 s2 = {0.f, 0.f};
; #pragma unroll
;     for (int d = 0; d < 4; ++d) {
;       f2 lo = __builtin_amdgcn_cvt_pk_f32_fp8((int)W[j][d], false);
;       f2 hi = __builtin_amdgcn_cvt_pk_f32_fp8((int)W[j][d], true);
;       s2 = lo * xf[2 * d] + s2;
;       s2 = hi * xf[2 * d + 1] + s2;
;     }
;     pv[j] = s2.x + s2.y;
;   }
	s_nop 0
	v_pk_fma_f32 v[230:231], v[232:233], v[212:213], v[230:231]
	v_cvt_pk_f32_fp8_e32 v[232:233], v16
	v_pk_fma_f32 v[230:231], v[234:235], v[214:215], v[230:231]
	v_cvt_pk_f32_fp8_sdwa v[234:235], v16 src0_sel:WORD_1
	v_pk_fma_f32 v[230:231], v[236:237], v[216:217], v[230:231]
	v_cvt_pk_f32_fp8_e32 v[236:237], v17
	v_pk_fma_f32 v[230:231], v[232:233], v[202:203], v[230:231]
	v_cvt_pk_f32_fp8_sdwa v[232:233], v18 src0_sel:WORD_1
	v_pk_fma_f32 v[230:231], v[234:235], v[204:205], v[230:231]
	v_cvt_pk_f32_fp8_e32 v[234:235], v19
	v_pk_fma_f32 v[230:231], v[236:237], v[206:207], v[230:231]
	v_cvt_pk_f32_fp8_sdwa v[236:237], v19 src0_sel:WORD_1
	v_pk_fma_f32 v[230:231], v[238:239], v[208:209], v[230:231]
	v_cvt_pk_f32_fp8_sdwa v[238:239], v21 src0_sel:WORD_1
	v_add_f32_e32 v173, v230, v231
	v_cvt_pk_f32_fp8_e32 v[230:231], v18
	v_pk_fma_f32 v[230:231], v[230:231], v[210:211], 0 op_sel_hi:[1,1,0]
	s_nop 0
	v_pk_fma_f32 v[230:231], v[232:233], v[212:213], v[230:231]
	v_cvt_pk_f32_fp8_e32 v[232:233], v20
	v_pk_fma_f32 v[230:231], v[234:235], v[214:215], v[230:231]
	v_cvt_pk_f32_fp8_sdwa v[234:235], v20 src0_sel:WORD_1
	v_pk_fma_f32 v[230:231], v[236:237], v[216:217], v[230:231]
	v_cvt_pk_f32_fp8_e32 v[236:237], v21
	v_pk_fma_f32 v[230:231], v[232:233], v[202:203], v[230:231]
	v_cvt_pk_f32_fp8_sdwa v[232:233], v22 src0_sel:WORD_1
	v_pk_fma_f32 v[230:231], v[234:235], v[204:205], v[230:231]
	v_cvt_pk_f32_fp8_e32 v[234:235], v23
	v_pk_fma_f32 v[230:231], v[236:237], v[206:207], v[230:231]
	v_cvt_pk_f32_fp8_sdwa v[236:237], v23 src0_sel:WORD_1
	v_pk_fma_f32 v[230:231], v[238:239], v[208:209], v[230:231]
	v_cvt_pk_f32_fp8_sdwa v[238:239], v25 src0_sel:WORD_1
	v_add_f32_e32 v175, v230, v231
	v_cvt_pk_f32_fp8_e32 v[230:231], v22
	v_pk_fma_f32 v[230:231], v[230:231], v[210:211], 0 op_sel_hi:[1,1,0]
	s_nop 0
	v_pk_fma_f32 v[230:231], v[232:233], v[212:213], v[230:231]
	v_cvt_pk_f32_fp8_e32 v[232:233], v24
	v_pk_fma_f32 v[230:231], v[234:235], v[214:215], v[230:231]
	v_cvt_pk_f32_fp8_sdwa v[234:235], v24 src0_sel:WORD_1
	v_pk_fma_f32 v[230:231], v[236:237], v[216:217], v[230:231]
	v_cvt_pk_f32_fp8_e32 v[236:237], v25
	v_pk_fma_f32 v[230:231], v[232:233], v[202:203], v[230:231]
	v_cvt_pk_f32_fp8_sdwa v[232:233], v26 src0_sel:WORD_1
	v_pk_fma_f32 v[230:231], v[234:235], v[204:205], v[230:231]
	v_cvt_pk_f32_fp8_e32 v[234:235], v27
	v_pk_fma_f32 v[230:231], v[236:237], v[206:207], v[230:231]
	v_cvt_pk_f32_fp8_sdwa v[236:237], v27 src0_sel:WORD_1
	v_pk_fma_f32 v[230:231], v[238:239], v[208:209], v[230:231]
	v_cvt_pk_f32_fp8_sdwa v[238:239], v29 src0_sel:WORD_1
	v_add_f32_e32 v177, v230, v231
	v_cvt_pk_f32_fp8_e32 v[230:231], v26
	v_pk_fma_f32 v[230:231], v[230:231], v[210:211], 0 op_sel_hi:[1,1,0]
	s_nop 0
	v_pk_fma_f32 v[230:231], v[232:233], v[212:213], v[230:231]
	v_cvt_pk_f32_fp8_e32 v[232:233], v28
	v_pk_fma_f32 v[230:231], v[234:235], v[214:215], v[230:231]
	v_cvt_pk_f32_fp8_sdwa v[234:235], v28 src0_sel:WORD_1
	v_pk_fma_f32 v[230:231], v[236:237], v[216:217], v[230:231]
	v_cvt_pk_f32_fp8_e32 v[236:237], v29
	v_pk_fma_f32 v[230:231], v[232:233], v[202:203], v[230:231]
	v_cvt_pk_f32_fp8_sdwa v[232:233], v30 src0_sel:WORD_1
	v_pk_fma_f32 v[230:231], v[234:235], v[204:205], v[230:231]
	v_cvt_pk_f32_fp8_e32 v[234:235], v31
	v_pk_fma_f32 v[230:231], v[236:237], v[206:207], v[230:231]
	v_cvt_pk_f32_fp8_sdwa v[236:237], v31 src0_sel:WORD_1
	v_pk_fma_f32 v[230:231], v[238:239], v[208:209], v[230:231]
	v_cvt_pk_f32_fp8_sdwa v[238:239], v33 src0_sel:WORD_1
	v_add_f32_e32 v179, v230, v231
	v_cvt_pk_f32_fp8_e32 v[230:231], v30
	v_pk_fma_f32 v[230:231], v[230:231], v[210:211], 0 op_sel_hi:[1,1,0]
	s_nop 0
	v_pk_fma_f32 v[230:231], v[232:233], v[212:213], v[230:231]
	v_cvt_pk_f32_fp8_e32 v[232:233], v32
	v_pk_fma_f32 v[230:231], v[234:235], v[214:215], v[230:231]
	v_cvt_pk_f32_fp8_sdwa v[234:235], v32 src0_sel:WORD_1
	v_pk_fma_f32 v[230:231], v[236:237], v[216:217], v[230:231]
	v_cvt_pk_f32_fp8_e32 v[236:237], v33
	v_pk_fma_f32 v[230:231], v[232:233], v[202:203], v[230:231]
	v_cvt_pk_f32_fp8_sdwa v[232:233], v34 src0_sel:WORD_1
	v_pk_fma_f32 v[230:231], v[234:235], v[204:205], v[230:231]
	v_cvt_pk_f32_fp8_e32 v[234:235], v35
	v_pk_fma_f32 v[230:231], v[236:237], v[206:207], v[230:231]
	v_cvt_pk_f32_fp8_sdwa v[236:237], v35 src0_sel:WORD_1
	v_pk_fma_f32 v[230:231], v[238:239], v[208:209], v[230:231]
	v_cvt_pk_f32_fp8_sdwa v[238:239], v37 src0_sel:WORD_1
	v_add_f32_e32 v181, v230, v231
	v_cvt_pk_f32_fp8_e32 v[230:231], v34
	v_pk_fma_f32 v[230:231], v[230:231], v[210:211], 0 op_sel_hi:[1,1,0]
	s_nop 0
	v_pk_fma_f32 v[230:231], v[232:233], v[212:213], v[230:231]
	v_cvt_pk_f32_fp8_e32 v[232:233], v36
	v_pk_fma_f32 v[230:231], v[234:235], v[214:215], v[230:231]
	v_cvt_pk_f32_fp8_sdwa v[234:235], v36 src0_sel:WORD_1
	v_pk_fma_f32 v[230:231], v[236:237], v[216:217], v[230:231]
	v_cvt_pk_f32_fp8_e32 v[236:237], v37
	v_pk_fma_f32 v[230:231], v[232:233], v[202:203], v[230:231]
	v_cvt_pk_f32_fp8_sdwa v[232:233], v38 src0_sel:WORD_1
	v_pk_fma_f32 v[230:231], v[234:235], v[204:205], v[230:231]
	v_cvt_pk_f32_fp8_e32 v[234:235], v39
	v_pk_fma_f32 v[230:231], v[236:237], v[206:207], v[230:231]
	v_cvt_pk_f32_fp8_sdwa v[236:237], v39 src0_sel:WORD_1
	v_pk_fma_f32 v[230:231], v[238:239], v[208:209], v[230:231]
	v_cvt_pk_f32_fp8_sdwa v[238:239], v41 src0_sel:WORD_1
	v_add_f32_e32 v183, v230, v231
	v_cvt_pk_f32_fp8_e32 v[230:231], v38
	v_pk_fma_f32 v[230:231], v[230:231], v[210:211], 0 op_sel_hi:[1,1,0]
	s_nop 0
	v_pk_fma_f32 v[230:231], v[232:233], v[212:213], v[230:231]
	v_cvt_pk_f32_fp8_e32 v[232:233], v40
	v_pk_fma_f32 v[230:231], v[234:235], v[214:215], v[230:231]
; DI void dn2_math(const u32x4 (&W)[16], u32x4 x0, u32x4 x1, float* __restrict__ parow, int lane) {
;     ...
; #pragma unroll
;   for (int j = 0; j < 16; ++j) {
;     f2 s2 = {0.f, 0.f};
; #pragma unroll
;     for (int d = 0; d < 4; ++d) {
;       f2 lo = __builtin_amdgcn_cvt_pk_f32_fp8((int)W[j][d], false);
;       f2 hi = __builtin_amdgcn_cvt_pk_f32_fp8((int)W[j][d], true);
;       s2 = lo * xf[2 * d] + s2;
;       s2 = hi * xf[2 * d + 1] + s2;
;     }
;     pv[j] = s2.x + s2.y;
;   }
	v_cvt_pk_f32_fp8_sdwa v[234:235], v40 src0_sel:WORD_1
	v_pk_fma_f32 v[230:231], v[236:237], v[216:217], v[230:231]
	v_cvt_pk_f32_fp8_e32 v[236:237], v41
	v_pk_fma_f32 v[230:231], v[232:233], v[202:203], v[230:231]
	v_cvt_pk_f32_fp8_sdwa v[232:233], v42 src0_sel:WORD_1
	v_pk_fma_f32 v[230:231], v[234:235], v[204:205], v[230:231]
	v_cvt_pk_f32_fp8_e32 v[234:235], v43
	v_pk_fma_f32 v[230:231], v[236:237], v[206:207], v[230:231]
	v_cvt_pk_f32_fp8_sdwa v[236:237], v43 src0_sel:WORD_1
	v_pk_fma_f32 v[230:231], v[238:239], v[208:209], v[230:231]
	v_cvt_pk_f32_fp8_sdwa v[238:239], v45 src0_sel:WORD_1
	v_add_f32_e32 v185, v230, v231
	v_cvt_pk_f32_fp8_e32 v[230:231], v42
	v_pk_fma_f32 v[230:231], v[230:231], v[210:211], 0 op_sel_hi:[1,1,0]
	s_nop 0
	v_pk_fma_f32 v[230:231], v[232:233], v[212:213], v[230:231]
	v_cvt_pk_f32_fp8_e32 v[232:233], v44
	v_pk_fma_f32 v[230:231], v[234:235], v[214:215], v[230:231]
	v_cvt_pk_f32_fp8_sdwa v[234:235], v44 src0_sel:WORD_1
	v_pk_fma_f32 v[230:231], v[236:237], v[216:217], v[230:231]
	v_cvt_pk_f32_fp8_e32 v[236:237], v45
	v_pk_fma_f32 v[230:231], v[232:233], v[202:203], v[230:231]
	v_cvt_pk_f32_fp8_sdwa v[232:233], v46 src0_sel:WORD_1
	v_pk_fma_f32 v[230:231], v[234:235], v[204:205], v[230:231]
	v_cvt_pk_f32_fp8_e32 v[234:235], v47
	v_pk_fma_f32 v[230:231], v[236:237], v[206:207], v[230:231]
	v_cvt_pk_f32_fp8_sdwa v[236:237], v47 src0_sel:WORD_1
	v_pk_fma_f32 v[230:231], v[238:239], v[208:209], v[230:231]
	v_cvt_pk_f32_fp8_sdwa v[238:239], v49 src0_sel:WORD_1
	v_add_f32_e32 v187, v230, v231
	v_cvt_pk_f32_fp8_e32 v[230:231], v46
	v_pk_fma_f32 v[230:231], v[230:231], v[210:211], 0 op_sel_hi:[1,1,0]
	s_nop 0
	v_pk_fma_f32 v[230:231], v[232:233], v[212:213], v[230:231]
	v_cvt_pk_f32_fp8_e32 v[232:233], v48
	v_pk_fma_f32 v[230:231], v[234:235], v[214:215], v[230:231]
	v_cvt_pk_f32_fp8_sdwa v[234:235], v48 src0_sel:WORD_1
	v_pk_fma_f32 v[230:231], v[236:237], v[216:217], v[230:231]
	v_cvt_pk_f32_fp8_e32 v[236:237], v49
	v_pk_fma_f32 v[230:231], v[232:233], v[202:203], v[230:231]
	v_cvt_pk_f32_fp8_sdwa v[232:233], v50 src0_sel:WORD_1
	v_pk_fma_f32 v[230:231], v[234:235], v[204:205], v[230:231]
	v_cvt_pk_f32_fp8_e32 v[234:235], v51
	v_pk_fma_f32 v[230:231], v[236:237], v[206:207], v[230:231]
	v_cvt_pk_f32_fp8_sdwa v[236:237], v51 src0_sel:WORD_1
	v_pk_fma_f32 v[230:231], v[238:239], v[208:209], v[230:231]
	v_cvt_pk_f32_fp8_sdwa v[238:239], v53 src0_sel:WORD_1
	v_add_f32_e32 v189, v230, v231
	v_cvt_pk_f32_fp8_e32 v[230:231], v50
	v_pk_fma_f32 v[230:231], v[230:231], v[210:211], 0 op_sel_hi:[1,1,0]
	s_nop 0
	v_pk_fma_f32 v[230:231], v[232:233], v[212:213], v[230:231]
	v_cvt_pk_f32_fp8_e32 v[232:233], v52
	v_pk_fma_f32 v[230:231], v[234:235], v[214:215], v[230:231]
	v_cvt_pk_f32_fp8_sdwa v[234:235], v52 src0_sel:WORD_1
	v_pk_fma_f32 v[230:231], v[236:237], v[216:217], v[230:231]
	v_cvt_pk_f32_fp8_e32 v[236:237], v53
	v_pk_fma_f32 v[230:231], v[232:233], v[202:203], v[230:231]
	v_cvt_pk_f32_fp8_sdwa v[232:233], v54 src0_sel:WORD_1
	v_pk_fma_f32 v[230:231], v[234:235], v[204:205], v[230:231]
	v_cvt_pk_f32_fp8_e32 v[234:235], v55
	v_pk_fma_f32 v[230:231], v[236:237], v[206:207], v[230:231]
	v_cvt_pk_f32_fp8_sdwa v[236:237], v55 src0_sel:WORD_1
	v_pk_fma_f32 v[230:231], v[238:239], v[208:209], v[230:231]
	v_cvt_pk_f32_fp8_sdwa v[238:239], v57 src0_sel:WORD_1
	v_add_f32_e32 v240, v230, v231
	v_cvt_pk_f32_fp8_e32 v[230:231], v54
	v_pk_fma_f32 v[230:231], v[230:231], v[210:211], 0 op_sel_hi:[1,1,0]
	s_nop 0
	v_pk_fma_f32 v[230:231], v[232:233], v[212:213], v[230:231]
	v_cvt_pk_f32_fp8_e32 v[232:233], v56
	v_pk_fma_f32 v[230:231], v[234:235], v[214:215], v[230:231]
	v_cvt_pk_f32_fp8_sdwa v[234:235], v56 src0_sel:WORD_1
	v_pk_fma_f32 v[230:231], v[236:237], v[216:217], v[230:231]
	v_cvt_pk_f32_fp8_e32 v[236:237], v57
	v_pk_fma_f32 v[230:231], v[232:233], v[202:203], v[230:231]
	v_cvt_pk_f32_fp8_sdwa v[232:233], v58 src0_sel:WORD_1
	v_pk_fma_f32 v[230:231], v[234:235], v[204:205], v[230:231]
	v_cvt_pk_f32_fp8_e32 v[234:235], v59
	v_pk_fma_f32 v[230:231], v[236:237], v[206:207], v[230:231]
	v_cvt_pk_f32_fp8_sdwa v[236:237], v59 src0_sel:WORD_1
	v_pk_fma_f32 v[230:231], v[238:239], v[208:209], v[230:231]
	v_cvt_pk_f32_fp8_sdwa v[238:239], v61 src0_sel:WORD_1
	v_add_f32_e32 v241, v230, v231
	v_cvt_pk_f32_fp8_e32 v[230:231], v58
	v_pk_fma_f32 v[230:231], v[230:231], v[210:211], 0 op_sel_hi:[1,1,0]
	s_nop 0
	v_pk_fma_f32 v[230:231], v[232:233], v[212:213], v[230:231]
	v_cvt_pk_f32_fp8_e32 v[232:233], v60
	v_pk_fma_f32 v[230:231], v[234:235], v[214:215], v[230:231]
	v_cvt_pk_f32_fp8_sdwa v[234:235], v60 src0_sel:WORD_1
	v_pk_fma_f32 v[230:231], v[236:237], v[216:217], v[230:231]
	v_cvt_pk_f32_fp8_e32 v[236:237], v61
	v_pk_fma_f32 v[230:231], v[232:233], v[202:203], v[230:231]
	v_cvt_pk_f32_fp8_sdwa v[232:233], v62 src0_sel:WORD_1
	v_pk_fma_f32 v[230:231], v[234:235], v[204:205], v[230:231]
	v_cvt_pk_f32_fp8_e32 v[234:235], v63
	v_pk_fma_f32 v[230:231], v[236:237], v[206:207], v[230:231]
	v_cvt_pk_f32_fp8_sdwa v[236:237], v63 src0_sel:WORD_1
	v_pk_fma_f32 v[230:231], v[238:239], v[208:209], v[230:231]
	s_nop 0
	v_add_f32_e32 v238, v230, v231
	v_cvt_pk_f32_fp8_e32 v[230:231], v62
	v_pk_fma_f32 v[210:211], v[230:231], v[210:211], 0 op_sel_hi:[1,1,0]
; DI void dn2_math(const u32x4 (&W)[16], u32x4 x0, u32x4 x1, float* __restrict__ parow, int lane) {
;     ...
;   const bool b2 = lane & 4, b1 = lane & 2, b0 = lane & 1;
;   float q8[8];
; #pragma unroll
;   for (int i = 0; i < 8; ++i) { float snd = b2 ? pv[i] : pv[i + 8]; float kp = b2 ? pv[i + 8] : pv[i]; q8[i] = kp + __shfl_xor(snd, 4); }
;   float q4[4];
; #pragma unroll
;   for (int i = 0; i < 4; ++i) { float snd = b1 ? q8[i] : q8[i + 4]; float kp = b1 ? q8[i + 4] : q8[i]; q4[i] = kp + __shfl_xor(snd, 2); }
;   float r2[2];
; #pragma unroll
;   for (int i = 0; i < 2; ++i) { float snd = b0 ? q4[i] : q4[i + 2]; float kp = b0 ? q4[i + 2] : q4[i]; r2[i] = kp + __shfl_xor(snd, 1); }
;   const int j0 = (b0 ? 2 : 0) + (b1 ? 4 : 0) + (b2 ? 8 : 0);
;   const int grp = lane >> 3;
;   parow[8 * j0 + grp] = r2[0];
;   parow[8 * (j0 + 1) + grp] = r2[1];
; }
; DI void peer_down2_phase(const Params& p, unsigned char* smem, int layer, const bf16* __restrict__ x1b, u32* ctr) {
;     ...
;         if (tl + 2 < 16) {
;           dn2_issue(WA, pl + (tl + 2) * 128, wbase, grp);
;           xa0 = *(const u32x4*)(xb0 + (size_t)(tl + 2) * 1024); xa1 = *(const u32x4*)(xb0 + (size_t)(tl + 2) * 1024 + 8);
;         }
	s_nop 0
	v_pk_fma_f32 v[210:211], v[232:233], v[212:213], v[210:211]
	v_cvt_pk_f32_fp8_e32 v[212:213], v64
	v_pk_fma_f32 v[210:211], v[234:235], v[214:215], v[210:211]
	v_cvt_pk_f32_fp8_sdwa v[214:215], v64 src0_sel:WORD_1
	v_pk_fma_f32 v[210:211], v[236:237], v[216:217], v[210:211]
	v_cvt_pk_f32_fp8_e32 v[216:217], v65
	v_cvt_pk_f32_fp8_sdwa v[230:231], v65 src0_sel:WORD_1
	v_pk_fma_f32 v[202:203], v[212:213], v[202:203], v[210:211]
	s_nop 0
	v_pk_fma_f32 v[202:203], v[214:215], v[204:205], v[202:203]
	v_pk_fma_f32 v[202:203], v[216:217], v[206:207], v[202:203]
	v_pk_fma_f32 v[202:203], v[230:231], v[208:209], v[202:203]
	v_add_f32_e32 v202, v202, v203
	s_nop 1
	v_add_f32_dpp v167, v167, v167 row_shl:4 row_mask:0xf bank_mask:0x5
	v_add_f32_dpp v173, v173, v173 row_shl:4 row_mask:0xf bank_mask:0x5
	v_add_f32_dpp v175, v175, v175 row_shl:4 row_mask:0xf bank_mask:0x5
	v_add_f32_dpp v169, v169, v169 row_shl:4 row_mask:0xf bank_mask:0x5
	v_add_f32_dpp v171, v171, v171 row_shl:4 row_mask:0xf bank_mask:0x5
	v_add_f32_dpp v177, v177, v177 row_shl:4 row_mask:0xf bank_mask:0x5
	v_add_f32_dpp v179, v179, v179 row_shl:4 row_mask:0xf bank_mask:0x5
	v_add_f32_dpp v181, v181, v181 row_shl:4 row_mask:0xf bank_mask:0x5
	v_add_f32_dpp v167, v183, v183 row_shr:4 row_mask:0xf bank_mask:0xa
	v_add_f32_dpp v173, v189, v189 row_shr:4 row_mask:0xf bank_mask:0xa
	v_add_f32_dpp v175, v240, v240 row_shr:4 row_mask:0xf bank_mask:0xa
	v_add_f32_dpp v169, v185, v185 row_shr:4 row_mask:0xf bank_mask:0xa
	v_add_f32_dpp v171, v187, v187 row_shr:4 row_mask:0xf bank_mask:0xa
	v_add_f32_dpp v177, v241, v241 row_shr:4 row_mask:0xf bank_mask:0xa
	v_add_f32_dpp v179, v238, v238 row_shr:4 row_mask:0xf bank_mask:0xa
	v_add_f32_dpp v181, v202, v202 row_shr:4 row_mask:0xf bank_mask:0xa
	s_nop 1
	v_add_f32_dpp v167, v167, v167 quad_perm:[2,3,0,1] row_mask:0xf bank_mask:0xf
	v_add_f32_dpp v171, v171, v171 quad_perm:[2,3,0,1] row_mask:0xf bank_mask:0xf
	v_add_f32_dpp v169, v169, v169 quad_perm:[2,3,0,1] row_mask:0xf bank_mask:0xf
	v_add_f32_dpp v173, v173, v173 quad_perm:[2,3,0,1] row_mask:0xf bank_mask:0xf
	v_add_f32_dpp v175, v175, v175 quad_perm:[2,3,0,1] row_mask:0xf bank_mask:0xf
	v_add_f32_dpp v179, v179, v179 quad_perm:[2,3,0,1] row_mask:0xf bank_mask:0xf
	v_add_f32_dpp v177, v177, v177 quad_perm:[2,3,0,1] row_mask:0xf bank_mask:0xf
	v_add_f32_dpp v181, v181, v181 quad_perm:[2,3,0,1] row_mask:0xf bank_mask:0xf
	v_cndmask_b32_e64 v167, v175, v167, s[12:13]
	v_cndmask_b32_e64 v171, v179, v171, s[12:13]
	v_cndmask_b32_e64 v169, v177, v169, s[12:13]
	v_cndmask_b32_e64 v173, v181, v173, s[12:13]
	s_nop 1
	v_add_f32_dpp v167, v167, v167 quad_perm:[1,0,3,2] row_mask:0xf bank_mask:0xf
	v_add_f32_dpp v169, v169, v169 quad_perm:[1,0,3,2] row_mask:0xf bank_mask:0xf
	v_add_f32_dpp v171, v171, v171 quad_perm:[1,0,3,2] row_mask:0xf bank_mask:0xf
	v_add_f32_dpp v173, v173, v173 quad_perm:[1,0,3,2] row_mask:0xf bank_mask:0xf
	v_cndmask_b32_e64 v167, v171, v167, s[14:15]
	v_cndmask_b32_e64 v169, v173, v169, s[14:15]
	global_store_dword v[200:201], v167, off offset:-512
	global_store_dword v[200:201], v169, off offset:-480
	s_cmp_gt_u32 s46, 13
	s_cselect_b64 s[28:29], -1, 0
	s_cbranch_scc1 .LBB0_693
	ds_read2_b32 v[2:3], v165 offset0:128 offset1:136
	ds_read2_b32 v[10:11], v165 offset0:144 offset1:152
	ds_read2_b32 v[18:19], v165 offset0:160 offset1:168
	ds_read2_b32 v[26:27], v165 offset0:176 offset1:184
	ds_read2_b32 v[34:35], v165 offset0:192 offset1:200
	ds_read2_b32 v[42:43], v165 offset0:208 offset1:216
	ds_read2_b32 v[50:51], v165 offset0:224 offset1:232
	ds_read2_b32 v[58:59], v165 offset0:240 offset1:248
	s_waitcnt lgkmcnt(7)
	v_lshl_add_u32 v6, v3, 10, v250
	v_lshl_add_u32 v2, v2, 10, v250
	global_load_dwordx4 v[2:5], v2, s[98:99]
	global_load_dwordx4 v[6:9], v6, s[98:99]
	s_waitcnt lgkmcnt(6)
	v_lshl_add_u32 v14, v11, 10, v250
	v_lshl_add_u32 v10, v10, 10, v250
	global_load_dwordx4 v[10:13], v10, s[98:99]
	global_load_dwordx4 v[14:17], v14, s[98:99]
	s_waitcnt lgkmcnt(5)
	v_lshl_add_u32 v22, v19, 10, v250
	v_lshl_add_u32 v18, v18, 10, v250
	global_load_dwordx4 v[18:21], v18, s[98:99]
	global_load_dwordx4 v[22:25], v22, s[98:99]
	s_waitcnt lgkmcnt(4)
	v_lshl_add_u32 v30, v27, 10, v250
	v_lshl_add_u32 v26, v26, 10, v250
	global_load_dwordx4 v[26:29], v26, s[98:99]
	global_load_dwordx4 v[30:33], v30, s[98:99]
	s_waitcnt lgkmcnt(3)
	v_lshl_add_u32 v38, v35, 10, v250
	v_lshl_add_u32 v34, v34, 10, v250
	global_load_dwordx4 v[34:37], v34, s[98:99]
	global_load_dwordx4 v[38:41], v38, s[98:99]
	s_waitcnt lgkmcnt(2)
	v_lshl_add_u32 v46, v43, 10, v250
	v_lshl_add_u32 v42, v42, 10, v250
	global_load_dwordx4 v[42:45], v42, s[98:99]
	global_load_dwordx4 v[46:49], v46, s[98:99]
	s_waitcnt lgkmcnt(1)
	v_lshl_add_u32 v54, v51, 10, v250
	v_lshl_add_u32 v50, v50, 10, v250
	global_load_dwordx4 v[50:53], v50, s[98:99]
	global_load_dwordx4 v[54:57], v54, s[98:99]
	s_waitcnt lgkmcnt(0)
	v_lshl_add_u32 v62, v59, 10, v250
	v_lshl_add_u32 v58, v58, 10, v250
	global_load_dwordx4 v[58:61], v58, s[98:99]
	global_load_dwordx4 v[62:65], v62, s[98:99]
	s_nop 0
	global_load_dwordx4 v[66:69], v[198:199], off offset:16
	global_load_dwordx4 v[70:73], v[198:199], off
	s_branch .LBB0_693

; DI void up_issue(u32x4 (&W)[16], u32 (&pj)[16], const u32* pl, const unsigned char* wbase, int grp) {
; #pragma unroll
;   for (int j = 0; j < 16; ++j) {
;     pj[j] = pl[8 * j + grp];
;     W[j] = *(const u32x4*)(wbase + (size_t)(pj[j] >> 16) * 1024);
;   }
; }
; DI void up_math(const u32x4 (&W)[16], const u32 (&pj)[16], float* __restrict__ yrow, int lane) {
;   f2 y[8];
; #pragma unroll
;   for (int i = 0; i < 8; ++i) y[i] = f2{0.f, 0.f};
; #pragma unroll
;   for (int j = 0; j < 16; ++j) {
;     const float h = __uint_as_float(pj[j] << 16);
;     const f2 hh = {h, h};
; #pragma unroll
;     for (int d = 0; d < 4; ++d) {
;       f2 lo = __builtin_amdgcn_cvt_pk_f32_fp8((int)W[j][d], false);
;       f2 hi = __builtin_amdgcn_cvt_pk_f32_fp8((int)W[j][d], true);
;       y[2 * d] = lo * hh + y[2 * d];
;       y[2 * d + 1] = hi * hh + y[2 * d + 1];
;     }
;   }
; DI void peer_up_phase(const Params& p, unsigned char* smem, int layer, u32* ctr) {
;     ...
;       for (int tl = 0; tl < 16; tl += 2) {
;         up_issue(WB, pB, pl + (tl + 1) * 128, wbase, grp);
;         __builtin_amdgcn_sched_barrier(0);
;         up_math(WA, pA, ybase + (size_t)tl * 1024, lane);
.LBB0_827:
	v_mov_b32_e32 v210, 0
	v_mov_b32_e32 v211, 0
	v_mov_b32_e32 v208, 0
	v_mov_b32_e32 v209, 0
	v_mov_b32_e32 v206, 0
	v_mov_b32_e32 v207, 0
	ds_read_u16_d16_hi v210, v145
	ds_read_u16_d16_hi v211, v145 offset:32
	ds_read_u16_d16_hi v208, v145 offset:64
	ds_read_u16_d16_hi v209, v145 offset:96
	ds_read_u16_d16_hi v206, v145 offset:128
	ds_read_u16_d16_hi v207, v145 offset:160
	ds_read_u16_d16_hi v204, v145 offset:192
	ds_read_u16_d16_hi v205, v145 offset:224
	ds_read_u16_d16_hi v202, v145 offset:256
	ds_read_u16_d16_hi v203, v145 offset:288
	ds_read_u16_d16_hi v200, v145 offset:320
	ds_read_u16_d16_hi v201, v145 offset:352
	ds_read_u16_d16_hi v198, v145 offset:384
	ds_read_u16_d16_hi v199, v145 offset:416
	ds_read_u16_d16_hi v196, v145 offset:448
	ds_read_u16_d16_hi v197, v145 offset:480
	ds_read_u16 v128, v145 offset:2
	ds_read_u16 v124, v145 offset:34
	ds_read_u16 v120, v145 offset:66
	ds_read_u16 v116, v145 offset:98
	ds_read_u16 v112, v145 offset:130
	ds_read_u16 v108, v145 offset:162
	ds_read_u16 v104, v145 offset:194
	ds_read_u16 v100, v145 offset:226
	ds_read_u16 v96, v145 offset:258
	ds_read_u16 v92, v145 offset:290
	ds_read_u16 v88, v145 offset:322
	ds_read_u16 v84, v145 offset:354
	ds_read_u16 v80, v145 offset:386
	ds_read_u16 v76, v145 offset:418
	ds_read_u16 v72, v145 offset:450
	ds_read_u16 v68, v145 offset:482
	s_waitcnt lgkmcnt(15)
	v_lshl_add_u32 v128, v128, 10, v250
	global_load_dwordx4 v[128:131], v128, s[98:99]
	s_waitcnt lgkmcnt(14)
	v_lshl_add_u32 v124, v124, 10, v250
	global_load_dwordx4 v[124:127], v124, s[98:99]
	s_waitcnt lgkmcnt(13)
	v_lshl_add_u32 v120, v120, 10, v250
	global_load_dwordx4 v[120:123], v120, s[98:99]
	s_waitcnt lgkmcnt(12)
	v_lshl_add_u32 v116, v116, 10, v250
	global_load_dwordx4 v[116:119], v116, s[98:99]
	s_waitcnt lgkmcnt(11)
	v_lshl_add_u32 v112, v112, 10, v250
	global_load_dwordx4 v[112:115], v112, s[98:99]
	s_waitcnt lgkmcnt(10)
	v_lshl_add_u32 v108, v108, 10, v250
	global_load_dwordx4 v[108:111], v108, s[98:99]
	s_waitcnt lgkmcnt(9)
	v_lshl_add_u32 v104, v104, 10, v250
	global_load_dwordx4 v[104:107], v104, s[98:99]
	s_waitcnt lgkmcnt(8)
	v_lshl_add_u32 v100, v100, 10, v250
	global_load_dwordx4 v[100:103], v100, s[98:99]
	s_waitcnt lgkmcnt(7)
	v_lshl_add_u32 v96, v96, 10, v250
	global_load_dwordx4 v[96:99], v96, s[98:99]
	s_waitcnt lgkmcnt(6)
	v_lshl_add_u32 v92, v92, 10, v250
	global_load_dwordx4 v[92:95], v92, s[98:99]
	s_waitcnt lgkmcnt(5)
	v_lshl_add_u32 v88, v88, 10, v250
	global_load_dwordx4 v[88:91], v88, s[98:99]
	s_waitcnt lgkmcnt(4)
	v_lshl_add_u32 v84, v84, 10, v250
	global_load_dwordx4 v[84:87], v84, s[98:99]
	s_waitcnt lgkmcnt(3)
	v_lshl_add_u32 v80, v80, 10, v250
	global_load_dwordx4 v[80:83], v80, s[98:99]
	s_waitcnt lgkmcnt(2)
	v_lshl_add_u32 v76, v76, 10, v250
	global_load_dwordx4 v[76:79], v76, s[98:99]
	s_waitcnt lgkmcnt(1)
	v_lshl_add_u32 v72, v72, 10, v250
	global_load_dwordx4 v[72:75], v72, s[98:99]
	s_waitcnt lgkmcnt(0)
	v_lshl_add_u32 v68, v68, 10, v250
	global_load_dwordx4 v[68:71], v68, s[98:99]
	s_waitcnt vmcnt(31)
	v_cvt_pk_f32_fp8_e32 v[216:217], v4
	v_cvt_pk_f32_fp8_sdwa v[226:227], v4 src0_sel:WORD_1
	v_cvt_pk_f32_fp8_e32 v[228:229], v5
	v_cvt_pk_f32_fp8_sdwa v[230:231], v5 src0_sel:WORD_1
	v_cvt_pk_f32_fp8_e32 v[232:233], v6
	v_cvt_pk_f32_fp8_sdwa v[234:235], v6 src0_sel:WORD_1
	v_cvt_pk_f32_fp8_e32 v[236:237], v7
	v_cvt_pk_f32_fp8_sdwa v[238:239], v7 src0_sel:WORD_1
	s_waitcnt vmcnt(30)
	v_cvt_pk_f32_fp8_e32 v[240:241], v8
	v_cvt_pk_f32_fp8_sdwa v[242:243], v8 src0_sel:WORD_1
	v_cvt_pk_f32_fp8_e32 v[244:245], v9
	v_cvt_pk_f32_fp8_sdwa v[246:247], v9 src0_sel:WORD_1
	v_pk_fma_f32 v[216:217], v[178:179], v[216:217], 0 op_sel_hi:[0,1,0]
	v_pk_fma_f32 v[226:227], v[178:179], v[226:227], 0 op_sel_hi:[0,1,0]
	v_pk_fma_f32 v[228:229], v[178:179], v[228:229], 0 op_sel_hi:[0,1,0]
	v_pk_fma_f32 v[230:231], v[178:179], v[230:231], 0 op_sel_hi:[0,1,0]
	v_pk_fma_f32 v[232:233], v[178:179], v[232:233], 0 op_sel_hi:[0,1,0]
	v_pk_fma_f32 v[234:235], v[178:179], v[234:235], 0 op_sel_hi:[0,1,0]
	v_pk_fma_f32 v[236:237], v[178:179], v[236:237], 0 op_sel_hi:[0,1,0]
	v_pk_fma_f32 v[238:239], v[178:179], v[238:239], 0 op_sel_hi:[0,1,0]
	v_pk_fma_f32 v[216:217], v[178:179], v[240:241], v[216:217] op_sel:[1,0,0] op_sel_hi:[1,1,1]
	v_cvt_pk_f32_fp8_e32 v[240:241], v10
	v_pk_fma_f32 v[226:227], v[178:179], v[242:243], v[226:227] op_sel:[1,0,0] op_sel_hi:[1,1,1]
	v_pk_fma_f32 v[228:229], v[178:179], v[244:245], v[228:229] op_sel:[1,0,0] op_sel_hi:[1,1,1]
	v_pk_fma_f32 v[230:231], v[178:179], v[246:247], v[230:231] op_sel:[1,0,0] op_sel_hi:[1,1,1]
	v_cvt_pk_f32_fp8_sdwa v[242:243], v10 src0_sel:WORD_1
	v_cvt_pk_f32_fp8_e32 v[244:245], v11
	v_cvt_pk_f32_fp8_sdwa v[246:247], v11 src0_sel:WORD_1
	v_pk_fma_f32 v[232:233], v[178:179], v[240:241], v[232:233] op_sel:[1,0,0] op_sel_hi:[1,1,1]
	s_waitcnt vmcnt(29)
	v_cvt_pk_f32_fp8_e32 v[240:241], v12
	v_pk_fma_f32 v[234:235], v[178:179], v[242:243], v[234:235] op_sel:[1,0,0] op_sel_hi:[1,1,1]
	v_pk_fma_f32 v[236:237], v[178:179], v[244:245], v[236:237] op_sel:[1,0,0] op_sel_hi:[1,1,1]
	v_pk_fma_f32 v[238:239], v[178:179], v[246:247], v[238:239] op_sel:[1,0,0] op_sel_hi:[1,1,1]
	v_cvt_pk_f32_fp8_sdwa v[242:243], v12 src0_sel:WORD_1
	v_cvt_pk_f32_fp8_e32 v[244:245], v13
	v_cvt_pk_f32_fp8_sdwa v[246:247], v13 src0_sel:WORD_1
	v_pk_fma_f32 v[216:217], v[180:181], v[240:241], v[216:217] op_sel_hi:[0,1,1]
	v_cvt_pk_f32_fp8_e32 v[240:241], v14
	v_pk_fma_f32 v[226:227], v[180:181], v[242:243], v[226:227] op_sel_hi:[0,1,1]
	v_pk_fma_f32 v[228:229], v[180:181], v[244:245], v[228:229] op_sel_hi:[0,1,1]
	v_pk_fma_f32 v[230:231], v[180:181], v[246:247], v[230:231] op_sel_hi:[0,1,1]
	v_cvt_pk_f32_fp8_sdwa v[242:243], v14 src0_sel:WORD_1
	v_cvt_pk_f32_fp8_e32 v[244:245], v15
	v_cvt_pk_f32_fp8_sdwa v[246:247], v15 src0_sel:WORD_1
	v_pk_fma_f32 v[232:233], v[180:181], v[240:241], v[232:233] op_sel_hi:[0,1,1]
	s_waitcnt vmcnt(28)
; DI void up_math(const u32x4 (&W)[16], const u32 (&pj)[16], float* __restrict__ yrow, int lane) {
;     ...
; #pragma unroll
;   for (int j = 0; j < 16; ++j) {
;     const float h = __uint_as_float(pj[j] << 16);
;     const f2 hh = {h, h};
; #pragma unroll
;     for (int d = 0; d < 4; ++d) {
;       f2 lo = __builtin_amdgcn_cvt_pk_f32_fp8((int)W[j][d], false);
;       f2 hi = __builtin_amdgcn_cvt_pk_f32_fp8((int)W[j][d], true);
;       y[2 * d] = lo * hh + y[2 * d];
;       y[2 * d + 1] = hi * hh + y[2 * d + 1];
;     }
;   }
	v_cvt_pk_f32_fp8_e32 v[240:241], v16
	v_pk_fma_f32 v[234:235], v[180:181], v[242:243], v[234:235] op_sel_hi:[0,1,1]
	v_pk_fma_f32 v[236:237], v[180:181], v[244:245], v[236:237] op_sel_hi:[0,1,1]
	v_pk_fma_f32 v[238:239], v[180:181], v[246:247], v[238:239] op_sel_hi:[0,1,1]
	v_cvt_pk_f32_fp8_sdwa v[242:243], v16 src0_sel:WORD_1
	v_cvt_pk_f32_fp8_e32 v[244:245], v17
	v_cvt_pk_f32_fp8_sdwa v[246:247], v17 src0_sel:WORD_1
	v_pk_fma_f32 v[216:217], v[180:181], v[240:241], v[216:217] op_sel:[1,0,0] op_sel_hi:[1,1,1]
	v_cvt_pk_f32_fp8_e32 v[240:241], v18
	v_pk_fma_f32 v[226:227], v[180:181], v[242:243], v[226:227] op_sel:[1,0,0] op_sel_hi:[1,1,1]
	v_pk_fma_f32 v[228:229], v[180:181], v[244:245], v[228:229] op_sel:[1,0,0] op_sel_hi:[1,1,1]
	v_pk_fma_f32 v[230:231], v[180:181], v[246:247], v[230:231] op_sel:[1,0,0] op_sel_hi:[1,1,1]
	v_cvt_pk_f32_fp8_sdwa v[242:243], v18 src0_sel:WORD_1
	v_cvt_pk_f32_fp8_e32 v[244:245], v19
	v_cvt_pk_f32_fp8_sdwa v[246:247], v19 src0_sel:WORD_1
	v_pk_fma_f32 v[232:233], v[180:181], v[240:241], v[232:233] op_sel:[1,0,0] op_sel_hi:[1,1,1]
	s_waitcnt vmcnt(27)
	v_cvt_pk_f32_fp8_e32 v[240:241], v20
	v_pk_fma_f32 v[234:235], v[180:181], v[242:243], v[234:235] op_sel:[1,0,0] op_sel_hi:[1,1,1]
	v_pk_fma_f32 v[236:237], v[180:181], v[244:245], v[236:237] op_sel:[1,0,0] op_sel_hi:[1,1,1]
	v_pk_fma_f32 v[238:239], v[180:181], v[246:247], v[238:239] op_sel:[1,0,0] op_sel_hi:[1,1,1]
	v_cvt_pk_f32_fp8_sdwa v[242:243], v20 src0_sel:WORD_1
	v_cvt_pk_f32_fp8_e32 v[244:245], v21
	v_cvt_pk_f32_fp8_sdwa v[246:247], v21 src0_sel:WORD_1
	v_pk_fma_f32 v[216:217], v[182:183], v[240:241], v[216:217] op_sel_hi:[0,1,1]
	v_cvt_pk_f32_fp8_e32 v[240:241], v22
	v_pk_fma_f32 v[226:227], v[182:183], v[242:243], v[226:227] op_sel_hi:[0,1,1]
	v_pk_fma_f32 v[228:229], v[182:183], v[244:245], v[228:229] op_sel_hi:[0,1,1]
	v_pk_fma_f32 v[230:231], v[182:183], v[246:247], v[230:231] op_sel_hi:[0,1,1]
	v_cvt_pk_f32_fp8_sdwa v[242:243], v22 src0_sel:WORD_1
	v_cvt_pk_f32_fp8_e32 v[244:245], v23
	v_cvt_pk_f32_fp8_sdwa v[246:247], v23 src0_sel:WORD_1
	v_pk_fma_f32 v[232:233], v[182:183], v[240:241], v[232:233] op_sel_hi:[0,1,1]
	s_waitcnt vmcnt(26)
	v_cvt_pk_f32_fp8_e32 v[240:241], v24
	v_pk_fma_f32 v[234:235], v[182:183], v[242:243], v[234:235] op_sel_hi:[0,1,1]
	v_pk_fma_f32 v[236:237], v[182:183], v[244:245], v[236:237] op_sel_hi:[0,1,1]
	v_pk_fma_f32 v[238:239], v[182:183], v[246:247], v[238:239] op_sel_hi:[0,1,1]
	v_cvt_pk_f32_fp8_sdwa v[242:243], v24 src0_sel:WORD_1
	v_cvt_pk_f32_fp8_e32 v[244:245], v25
	v_cvt_pk_f32_fp8_sdwa v[246:247], v25 src0_sel:WORD_1
	v_pk_fma_f32 v[216:217], v[182:183], v[240:241], v[216:217] op_sel:[1,0,0] op_sel_hi:[1,1,1]
	v_cvt_pk_f32_fp8_e32 v[240:241], v26
	v_pk_fma_f32 v[226:227], v[182:183], v[242:243], v[226:227] op_sel:[1,0,0] op_sel_hi:[1,1,1]
	v_pk_fma_f32 v[228:229], v[182:183], v[244:245], v[228:229] op_sel:[1,0,0] op_sel_hi:[1,1,1]
	v_pk_fma_f32 v[230:231], v[182:183], v[246:247], v[230:231] op_sel:[1,0,0] op_sel_hi:[1,1,1]
	v_cvt_pk_f32_fp8_sdwa v[242:243], v26 src0_sel:WORD_1
	v_cvt_pk_f32_fp8_e32 v[244:245], v27
	v_cvt_pk_f32_fp8_sdwa v[246:247], v27 src0_sel:WORD_1
	v_pk_fma_f32 v[232:233], v[182:183], v[240:241], v[232:233] op_sel:[1,0,0] op_sel_hi:[1,1,1]
	s_waitcnt vmcnt(25)
	v_cvt_pk_f32_fp8_e32 v[240:241], v28
	v_pk_fma_f32 v[234:235], v[182:183], v[242:243], v[234:235] op_sel:[1,0,0] op_sel_hi:[1,1,1]
	v_pk_fma_f32 v[236:237], v[182:183], v[244:245], v[236:237] op_sel:[1,0,0] op_sel_hi:[1,1,1]
	v_pk_fma_f32 v[238:239], v[182:183], v[246:247], v[238:239] op_sel:[1,0,0] op_sel_hi:[1,1,1]
	v_cvt_pk_f32_fp8_sdwa v[242:243], v28 src0_sel:WORD_1
	v_cvt_pk_f32_fp8_e32 v[244:245], v29
	v_cvt_pk_f32_fp8_sdwa v[246:247], v29 src0_sel:WORD_1
	v_pk_fma_f32 v[216:217], v[184:185], v[240:241], v[216:217] op_sel_hi:[0,1,1]
	v_cvt_pk_f32_fp8_e32 v[240:241], v30
	v_pk_fma_f32 v[226:227], v[184:185], v[242:243], v[226:227] op_sel_hi:[0,1,1]
	v_pk_fma_f32 v[228:229], v[184:185], v[244:245], v[228:229] op_sel_hi:[0,1,1]
	v_pk_fma_f32 v[230:231], v[184:185], v[246:247], v[230:231] op_sel_hi:[0,1,1]
	v_cvt_pk_f32_fp8_sdwa v[242:243], v30 src0_sel:WORD_1
	v_cvt_pk_f32_fp8_e32 v[244:245], v31
	v_cvt_pk_f32_fp8_sdwa v[246:247], v31 src0_sel:WORD_1
	v_pk_fma_f32 v[232:233], v[184:185], v[240:241], v[232:233] op_sel_hi:[0,1,1]
	s_waitcnt vmcnt(24)
	v_cvt_pk_f32_fp8_e32 v[240:241], v32
	v_pk_fma_f32 v[234:235], v[184:185], v[242:243], v[234:235] op_sel_hi:[0,1,1]
	v_pk_fma_f32 v[236:237], v[184:185], v[244:245], v[236:237] op_sel_hi:[0,1,1]
	v_pk_fma_f32 v[238:239], v[184:185], v[246:247], v[238:239] op_sel_hi:[0,1,1]
	v_cvt_pk_f32_fp8_sdwa v[242:243], v32 src0_sel:WORD_1
	v_cvt_pk_f32_fp8_e32 v[244:245], v33
	v_cvt_pk_f32_fp8_sdwa v[246:247], v33 src0_sel:WORD_1
	v_pk_fma_f32 v[216:217], v[184:185], v[240:241], v[216:217] op_sel:[1,0,0] op_sel_hi:[1,1,1]
	v_cvt_pk_f32_fp8_e32 v[240:241], v34
	v_pk_fma_f32 v[226:227], v[184:185], v[242:243], v[226:227] op_sel:[1,0,0] op_sel_hi:[1,1,1]
	v_pk_fma_f32 v[228:229], v[184:185], v[244:245], v[228:229] op_sel:[1,0,0] op_sel_hi:[1,1,1]
	v_pk_fma_f32 v[230:231], v[184:185], v[246:247], v[230:231] op_sel:[1,0,0] op_sel_hi:[1,1,1]
	v_cvt_pk_f32_fp8_sdwa v[242:243], v34 src0_sel:WORD_1
	v_cvt_pk_f32_fp8_e32 v[244:245], v35
	v_cvt_pk_f32_fp8_sdwa v[246:247], v35 src0_sel:WORD_1
	v_pk_fma_f32 v[232:233], v[184:185], v[240:241], v[232:233] op_sel:[1,0,0] op_sel_hi:[1,1,1]
	s_waitcnt vmcnt(23)
; DI void up_math(const u32x4 (&W)[16], const u32 (&pj)[16], float* __restrict__ yrow, int lane) {
;     ...
; #pragma unroll
;   for (int j = 0; j < 16; ++j) {
;     const float h = __uint_as_float(pj[j] << 16);
;     const f2 hh = {h, h};
; #pragma unroll
;     for (int d = 0; d < 4; ++d) {
;       f2 lo = __builtin_amdgcn_cvt_pk_f32_fp8((int)W[j][d], false);
;       f2 hi = __builtin_amdgcn_cvt_pk_f32_fp8((int)W[j][d], true);
;       y[2 * d] = lo * hh + y[2 * d];
;       y[2 * d + 1] = hi * hh + y[2 * d + 1];
;     }
;   }
	v_cvt_pk_f32_fp8_e32 v[240:241], v36
	v_pk_fma_f32 v[234:235], v[184:185], v[242:243], v[234:235] op_sel:[1,0,0] op_sel_hi:[1,1,1]
	v_pk_fma_f32 v[236:237], v[184:185], v[244:245], v[236:237] op_sel:[1,0,0] op_sel_hi:[1,1,1]
	v_pk_fma_f32 v[238:239], v[184:185], v[246:247], v[238:239] op_sel:[1,0,0] op_sel_hi:[1,1,1]
	v_cvt_pk_f32_fp8_sdwa v[242:243], v36 src0_sel:WORD_1
	v_cvt_pk_f32_fp8_e32 v[244:245], v37
	v_cvt_pk_f32_fp8_sdwa v[246:247], v37 src0_sel:WORD_1
	v_pk_fma_f32 v[216:217], v[186:187], v[240:241], v[216:217] op_sel_hi:[0,1,1]
	v_cvt_pk_f32_fp8_e32 v[240:241], v38
	v_pk_fma_f32 v[226:227], v[186:187], v[242:243], v[226:227] op_sel_hi:[0,1,1]
	v_pk_fma_f32 v[228:229], v[186:187], v[244:245], v[228:229] op_sel_hi:[0,1,1]
	v_pk_fma_f32 v[230:231], v[186:187], v[246:247], v[230:231] op_sel_hi:[0,1,1]
	v_cvt_pk_f32_fp8_sdwa v[242:243], v38 src0_sel:WORD_1
	v_cvt_pk_f32_fp8_e32 v[244:245], v39
	v_cvt_pk_f32_fp8_sdwa v[246:247], v39 src0_sel:WORD_1
	v_pk_fma_f32 v[232:233], v[186:187], v[240:241], v[232:233] op_sel_hi:[0,1,1]
	s_waitcnt vmcnt(22)
	v_cvt_pk_f32_fp8_e32 v[240:241], v40
	v_pk_fma_f32 v[234:235], v[186:187], v[242:243], v[234:235] op_sel_hi:[0,1,1]
	v_pk_fma_f32 v[236:237], v[186:187], v[244:245], v[236:237] op_sel_hi:[0,1,1]
	v_pk_fma_f32 v[238:239], v[186:187], v[246:247], v[238:239] op_sel_hi:[0,1,1]
	v_cvt_pk_f32_fp8_sdwa v[242:243], v40 src0_sel:WORD_1
	v_cvt_pk_f32_fp8_e32 v[244:245], v41
	v_cvt_pk_f32_fp8_sdwa v[246:247], v41 src0_sel:WORD_1
	v_pk_fma_f32 v[216:217], v[186:187], v[240:241], v[216:217] op_sel:[1,0,0] op_sel_hi:[1,1,1]
	v_cvt_pk_f32_fp8_e32 v[240:241], v42
	v_pk_fma_f32 v[226:227], v[186:187], v[242:243], v[226:227] op_sel:[1,0,0] op_sel_hi:[1,1,1]
	v_pk_fma_f32 v[228:229], v[186:187], v[244:245], v[228:229] op_sel:[1,0,0] op_sel_hi:[1,1,1]
	v_pk_fma_f32 v[230:231], v[186:187], v[246:247], v[230:231] op_sel:[1,0,0] op_sel_hi:[1,1,1]
	v_cvt_pk_f32_fp8_sdwa v[242:243], v42 src0_sel:WORD_1
	v_cvt_pk_f32_fp8_e32 v[244:245], v43
	v_cvt_pk_f32_fp8_sdwa v[246:247], v43 src0_sel:WORD_1
	v_pk_fma_f32 v[232:233], v[186:187], v[240:241], v[232:233] op_sel:[1,0,0] op_sel_hi:[1,1,1]
	s_waitcnt vmcnt(21)
	v_cvt_pk_f32_fp8_e32 v[240:241], v44
	v_pk_fma_f32 v[234:235], v[186:187], v[242:243], v[234:235] op_sel:[1,0,0] op_sel_hi:[1,1,1]
	v_pk_fma_f32 v[236:237], v[186:187], v[244:245], v[236:237] op_sel:[1,0,0] op_sel_hi:[1,1,1]
	v_pk_fma_f32 v[238:239], v[186:187], v[246:247], v[238:239] op_sel:[1,0,0] op_sel_hi:[1,1,1]
	v_cvt_pk_f32_fp8_sdwa v[242:243], v44 src0_sel:WORD_1
	v_cvt_pk_f32_fp8_e32 v[244:245], v45
	v_cvt_pk_f32_fp8_sdwa v[246:247], v45 src0_sel:WORD_1
	v_pk_fma_f32 v[216:217], v[190:191], v[240:241], v[216:217] op_sel_hi:[0,1,1]
	v_cvt_pk_f32_fp8_e32 v[240:241], v46
	v_pk_fma_f32 v[226:227], v[190:191], v[242:243], v[226:227] op_sel_hi:[0,1,1]
	v_pk_fma_f32 v[228:229], v[190:191], v[244:245], v[228:229] op_sel_hi:[0,1,1]
	v_pk_fma_f32 v[230:231], v[190:191], v[246:247], v[230:231] op_sel_hi:[0,1,1]
	v_cvt_pk_f32_fp8_sdwa v[242:243], v46 src0_sel:WORD_1
	v_cvt_pk_f32_fp8_e32 v[244:245], v47
	v_cvt_pk_f32_fp8_sdwa v[246:247], v47 src0_sel:WORD_1
	v_pk_fma_f32 v[232:233], v[190:191], v[240:241], v[232:233] op_sel_hi:[0,1,1]
	s_waitcnt vmcnt(20)
	v_cvt_pk_f32_fp8_e32 v[240:241], v48
	v_pk_fma_f32 v[234:235], v[190:191], v[242:243], v[234:235] op_sel_hi:[0,1,1]
	v_pk_fma_f32 v[236:237], v[190:191], v[244:245], v[236:237] op_sel_hi:[0,1,1]
	v_pk_fma_f32 v[238:239], v[190:191], v[246:247], v[238:239] op_sel_hi:[0,1,1]
	v_cvt_pk_f32_fp8_sdwa v[242:243], v48 src0_sel:WORD_1
	v_cvt_pk_f32_fp8_e32 v[244:245], v49
	v_cvt_pk_f32_fp8_sdwa v[246:247], v49 src0_sel:WORD_1
	v_pk_fma_f32 v[216:217], v[190:191], v[240:241], v[216:217] op_sel:[1,0,0] op_sel_hi:[1,1,1]
	v_cvt_pk_f32_fp8_e32 v[240:241], v50
	v_pk_fma_f32 v[226:227], v[190:191], v[242:243], v[226:227] op_sel:[1,0,0] op_sel_hi:[1,1,1]
	v_pk_fma_f32 v[228:229], v[190:191], v[244:245], v[228:229] op_sel:[1,0,0] op_sel_hi:[1,1,1]
	v_pk_fma_f32 v[230:231], v[190:191], v[246:247], v[230:231] op_sel:[1,0,0] op_sel_hi:[1,1,1]
	v_cvt_pk_f32_fp8_sdwa v[242:243], v50 src0_sel:WORD_1
	v_cvt_pk_f32_fp8_e32 v[244:245], v51
	v_cvt_pk_f32_fp8_sdwa v[246:247], v51 src0_sel:WORD_1
	v_pk_fma_f32 v[232:233], v[190:191], v[240:241], v[232:233] op_sel:[1,0,0] op_sel_hi:[1,1,1]
	s_waitcnt vmcnt(19)
	v_cvt_pk_f32_fp8_e32 v[240:241], v52
	v_pk_fma_f32 v[234:235], v[190:191], v[242:243], v[234:235] op_sel:[1,0,0] op_sel_hi:[1,1,1]
	v_pk_fma_f32 v[236:237], v[190:191], v[244:245], v[236:237] op_sel:[1,0,0] op_sel_hi:[1,1,1]
	v_pk_fma_f32 v[238:239], v[190:191], v[246:247], v[238:239] op_sel:[1,0,0] op_sel_hi:[1,1,1]
	v_cvt_pk_f32_fp8_sdwa v[242:243], v52 src0_sel:WORD_1
	v_cvt_pk_f32_fp8_e32 v[244:245], v53
	v_cvt_pk_f32_fp8_sdwa v[246:247], v53 src0_sel:WORD_1
	v_pk_fma_f32 v[216:217], v[192:193], v[240:241], v[216:217] op_sel_hi:[0,1,1]
	v_cvt_pk_f32_fp8_e32 v[240:241], v54
	v_pk_fma_f32 v[226:227], v[192:193], v[242:243], v[226:227] op_sel_hi:[0,1,1]
	v_pk_fma_f32 v[228:229], v[192:193], v[244:245], v[228:229] op_sel_hi:[0,1,1]
	v_pk_fma_f32 v[230:231], v[192:193], v[246:247], v[230:231] op_sel_hi:[0,1,1]
	v_cvt_pk_f32_fp8_sdwa v[242:243], v54 src0_sel:WORD_1
	v_cvt_pk_f32_fp8_e32 v[244:245], v55
	v_cvt_pk_f32_fp8_sdwa v[246:247], v55 src0_sel:WORD_1
	v_pk_fma_f32 v[232:233], v[192:193], v[240:241], v[232:233] op_sel_hi:[0,1,1]
	s_waitcnt vmcnt(18)
; DI void up_math(const u32x4 (&W)[16], const u32 (&pj)[16], float* __restrict__ yrow, int lane) {
;     ...
;   const bool b5 = lane & 32, b4 = lane & 16, b3 = lane & 8;
;   f2 q4[4];
; #pragma unroll
;   for (int i = 0; i < 4; ++i) {
;     f2 snd = b5 ? y[i] : y[i + 4]; f2 kp = b5 ? y[i + 4] : y[i];
;     q4[i] = f2{kp.x + __shfl_xor(snd.x, 32), kp.y + __shfl_xor(snd.y, 32)};
;   }
;   f2 r2[2];
; #pragma unroll
;   for (int i = 0; i < 2; ++i) {
;     f2 snd = b4 ? q4[i] : q4[i + 2]; f2 kp = b4 ? q4[i + 2] : q4[i];
;     r2[i] = f2{kp.x + __shfl_xor(snd.x, 16), kp.y + __shfl_xor(snd.y, 16)};
;   }
;   f2 a;
;   { f2 snd = b3 ? r2[0] : r2[1]; f2 kp = b3 ? r2[1] : r2[0]; a = f2{kp.x + __shfl_xor(snd.x, 8), kp.y + __shfl_xor(snd.y, 8)}; }
;   const int ci = (b5 ? 4 : 0) + (b4 ? 2 : 0) + (b3 ? 1 : 0);
;   *(float2*)(yrow + (lane & 7) * 16 + 2 * ci) = make_float2(a.x, a.y);
; DI void peer_up_phase(const Params& p, unsigned char* smem, int layer, u32* ctr) {
;     ...
;         __builtin_amdgcn_sched_barrier(0);
;         if (tl + 2 < 16) up_issue(WA, pA, pl + (tl + 2) * 128, wbase, grp);
	v_cvt_pk_f32_fp8_e32 v[240:241], v56
	v_pk_fma_f32 v[234:235], v[192:193], v[242:243], v[234:235] op_sel_hi:[0,1,1]
	v_pk_fma_f32 v[236:237], v[192:193], v[244:245], v[236:237] op_sel_hi:[0,1,1]
	v_pk_fma_f32 v[238:239], v[192:193], v[246:247], v[238:239] op_sel_hi:[0,1,1]
	v_cvt_pk_f32_fp8_sdwa v[242:243], v56 src0_sel:WORD_1
	v_cvt_pk_f32_fp8_e32 v[244:245], v57
	v_cvt_pk_f32_fp8_sdwa v[246:247], v57 src0_sel:WORD_1
	v_pk_fma_f32 v[216:217], v[192:193], v[240:241], v[216:217] op_sel:[1,0,0] op_sel_hi:[1,1,1]
	v_cvt_pk_f32_fp8_e32 v[240:241], v58
	v_pk_fma_f32 v[226:227], v[192:193], v[242:243], v[226:227] op_sel:[1,0,0] op_sel_hi:[1,1,1]
	v_pk_fma_f32 v[228:229], v[192:193], v[244:245], v[228:229] op_sel:[1,0,0] op_sel_hi:[1,1,1]
	v_pk_fma_f32 v[230:231], v[192:193], v[246:247], v[230:231] op_sel:[1,0,0] op_sel_hi:[1,1,1]
	v_cvt_pk_f32_fp8_sdwa v[242:243], v58 src0_sel:WORD_1
	v_cvt_pk_f32_fp8_e32 v[244:245], v59
	v_cvt_pk_f32_fp8_sdwa v[246:247], v59 src0_sel:WORD_1
	v_pk_fma_f32 v[232:233], v[192:193], v[240:241], v[232:233] op_sel:[1,0,0] op_sel_hi:[1,1,1]
	s_waitcnt vmcnt(17)
	v_cvt_pk_f32_fp8_e32 v[240:241], v60
	v_pk_fma_f32 v[234:235], v[192:193], v[242:243], v[234:235] op_sel:[1,0,0] op_sel_hi:[1,1,1]
	v_pk_fma_f32 v[236:237], v[192:193], v[244:245], v[236:237] op_sel:[1,0,0] op_sel_hi:[1,1,1]
	v_pk_fma_f32 v[238:239], v[192:193], v[246:247], v[238:239] op_sel:[1,0,0] op_sel_hi:[1,1,1]
	v_cvt_pk_f32_fp8_sdwa v[242:243], v60 src0_sel:WORD_1
	v_cvt_pk_f32_fp8_e32 v[244:245], v61
	v_cvt_pk_f32_fp8_sdwa v[246:247], v61 src0_sel:WORD_1
	v_pk_fma_f32 v[216:217], v[194:195], v[240:241], v[216:217] op_sel_hi:[0,1,1]
	v_cvt_pk_f32_fp8_e32 v[240:241], v62
	v_pk_fma_f32 v[226:227], v[194:195], v[242:243], v[226:227] op_sel_hi:[0,1,1]
	v_pk_fma_f32 v[228:229], v[194:195], v[244:245], v[228:229] op_sel_hi:[0,1,1]
	v_pk_fma_f32 v[230:231], v[194:195], v[246:247], v[230:231] op_sel_hi:[0,1,1]
	v_cvt_pk_f32_fp8_sdwa v[242:243], v62 src0_sel:WORD_1
	v_cvt_pk_f32_fp8_e32 v[244:245], v63
	v_cvt_pk_f32_fp8_sdwa v[246:247], v63 src0_sel:WORD_1
	v_pk_fma_f32 v[232:233], v[194:195], v[240:241], v[232:233] op_sel_hi:[0,1,1]
	s_waitcnt vmcnt(16)
	v_cvt_pk_f32_fp8_e32 v[240:241], v64
	v_pk_fma_f32 v[234:235], v[194:195], v[242:243], v[234:235] op_sel_hi:[0,1,1]
	v_pk_fma_f32 v[236:237], v[194:195], v[244:245], v[236:237] op_sel_hi:[0,1,1]
	v_pk_fma_f32 v[238:239], v[194:195], v[246:247], v[238:239] op_sel_hi:[0,1,1]
	v_cvt_pk_f32_fp8_sdwa v[242:243], v64 src0_sel:WORD_1
	v_cvt_pk_f32_fp8_e32 v[244:245], v65
	v_cvt_pk_f32_fp8_sdwa v[246:247], v65 src0_sel:WORD_1
	v_pk_fma_f32 v[216:217], v[194:195], v[240:241], v[216:217] op_sel:[1,0,0] op_sel_hi:[1,1,1]
	v_cvt_pk_f32_fp8_e32 v[240:241], v66
	v_pk_fma_f32 v[226:227], v[194:195], v[242:243], v[226:227] op_sel:[1,0,0] op_sel_hi:[1,1,1]
	v_pk_fma_f32 v[228:229], v[194:195], v[244:245], v[228:229] op_sel:[1,0,0] op_sel_hi:[1,1,1]
	v_pk_fma_f32 v[230:231], v[194:195], v[246:247], v[230:231] op_sel:[1,0,0] op_sel_hi:[1,1,1]
	v_cvt_pk_f32_fp8_sdwa v[242:243], v66 src0_sel:WORD_1
	v_cvt_pk_f32_fp8_e32 v[244:245], v67
	v_cvt_pk_f32_fp8_sdwa v[246:247], v67 src0_sel:WORD_1
	v_pk_fma_f32 v[232:233], v[194:195], v[240:241], v[232:233] op_sel:[1,0,0] op_sel_hi:[1,1,1]
	v_pk_fma_f32 v[234:235], v[194:195], v[242:243], v[234:235] op_sel:[1,0,0] op_sel_hi:[1,1,1]
	v_pk_fma_f32 v[236:237], v[194:195], v[244:245], v[236:237] op_sel:[1,0,0] op_sel_hi:[1,1,1]
	v_pk_fma_f32 v[238:239], v[194:195], v[246:247], v[238:239] op_sel:[1,0,0] op_sel_hi:[1,1,1]
	s_nop 1
	v_permlane32_swap_b32_e32 v216, v232
	v_permlane32_swap_b32_e32 v217, v233
	v_permlane32_swap_b32_e32 v228, v236
	v_permlane32_swap_b32_e32 v229, v237
	v_permlane32_swap_b32_e32 v226, v234
	v_permlane32_swap_b32_e32 v227, v235
	v_permlane32_swap_b32_e32 v230, v238
	v_permlane32_swap_b32_e32 v231, v239
	v_pk_add_f32 v[216:217], v[216:217], v[232:233]
	v_pk_add_f32 v[228:229], v[228:229], v[236:237]
	v_pk_add_f32 v[226:227], v[226:227], v[234:235]
	v_pk_add_f32 v[230:231], v[230:231], v[238:239]
	s_nop 1
	v_permlane16_swap_b32_e32 v216, v228
	v_permlane16_swap_b32_e32 v217, v229
	v_permlane16_swap_b32_e32 v226, v230
	v_permlane16_swap_b32_e32 v227, v231
	v_pk_add_f32 v[216:217], v[216:217], v[228:229]
	v_pk_add_f32 v[226:227], v[226:227], v[230:231]
	s_nop 0
	v_cndmask_b32_e64 v132, v217, v227, s[14:15]
	v_cndmask_b32_e64 v147, v216, v226, s[14:15]
	ds_bpermute_b32 v228, v143, v147
	ds_bpermute_b32 v229, v143, v132
	v_cndmask_b32_e64 v217, v227, v217, s[14:15]
	v_cndmask_b32_e64 v216, v226, v216, s[14:15]
	s_waitcnt lgkmcnt(0)
	v_pk_add_f32 v[216:217], v[216:217], v[228:229]
	global_store_dwordx2 v[188:189], v[216:217], off
	s_cmp_gt_u32 s44, 13
	s_cselect_b64 s[28:29], -1, 0
	s_cbranch_scc1 .LBB0_826
; DI void up_issue(u32x4 (&W)[16], u32 (&pj)[16], const u32* pl, const unsigned char* wbase, int grp) {
; #pragma unroll
;   for (int j = 0; j < 16; ++j) {
;     pj[j] = pl[8 * j + grp];
;     W[j] = *(const u32x4*)(wbase + (size_t)(pj[j] >> 16) * 1024);
;   }
; }
; DI void peer_up_phase(const Params& p, unsigned char* smem, int layer, u32* ctr) {
;     ...
;         if (tl + 2 < 16) up_issue(WA, pA, pl + (tl + 2) * 128, wbase, grp);
	ds_read_u16_d16_hi v178, v145 offset:512
	ds_read_u16_d16_hi v179, v145 offset:544
	ds_read_u16_d16_hi v180, v145 offset:576
	ds_read_u16_d16_hi v181, v145 offset:608
	ds_read_u16_d16_hi v182, v145 offset:640
	ds_read_u16_d16_hi v183, v145 offset:672
	ds_read_u16_d16_hi v184, v145 offset:704
	ds_read_u16_d16_hi v185, v145 offset:736
	ds_read_u16_d16_hi v186, v145 offset:768
	ds_read_u16_d16_hi v187, v145 offset:800
	ds_read_u16_d16_hi v190, v145 offset:832
	ds_read_u16_d16_hi v191, v145 offset:864
	ds_read_u16_d16_hi v192, v145 offset:896
	ds_read_u16_d16_hi v193, v145 offset:928
	ds_read_u16_d16_hi v194, v145 offset:960
	ds_read_u16_d16_hi v195, v145 offset:992
	ds_read_u16 v4, v145 offset:514
	ds_read_u16 v8, v145 offset:546
	ds_read_u16 v12, v145 offset:578
	ds_read_u16 v16, v145 offset:610
	ds_read_u16 v20, v145 offset:642
	ds_read_u16 v24, v145 offset:674
	ds_read_u16 v28, v145 offset:706
	ds_read_u16 v32, v145 offset:738
	ds_read_u16 v36, v145 offset:770
	ds_read_u16 v40, v145 offset:802
	ds_read_u16 v44, v145 offset:834
	ds_read_u16 v48, v145 offset:866
	ds_read_u16 v52, v145 offset:898
	ds_read_u16 v56, v145 offset:930
	ds_read_u16 v60, v145 offset:962
	ds_read_u16 v64, v145 offset:994
	s_waitcnt lgkmcnt(15)
	v_lshl_add_u32 v4, v4, 10, v250
	global_load_dwordx4 v[4:7], v4, s[98:99]
	s_waitcnt lgkmcnt(14)
	v_lshl_add_u32 v8, v8, 10, v250
	global_load_dwordx4 v[8:11], v8, s[98:99]
	s_waitcnt lgkmcnt(13)
	v_lshl_add_u32 v12, v12, 10, v250
	global_load_dwordx4 v[12:15], v12, s[98:99]
	s_waitcnt lgkmcnt(12)
	v_lshl_add_u32 v16, v16, 10, v250
	global_load_dwordx4 v[16:19], v16, s[98:99]
	s_waitcnt lgkmcnt(11)
	v_lshl_add_u32 v20, v20, 10, v250
	global_load_dwordx4 v[20:23], v20, s[98:99]
	s_waitcnt lgkmcnt(10)
	v_lshl_add_u32 v24, v24, 10, v250
	global_load_dwordx4 v[24:27], v24, s[98:99]
	s_waitcnt lgkmcnt(9)
	v_lshl_add_u32 v28, v28, 10, v250
	global_load_dwordx4 v[28:31], v28, s[98:99]
	s_waitcnt lgkmcnt(8)
	v_lshl_add_u32 v32, v32, 10, v250
	global_load_dwordx4 v[32:35], v32, s[98:99]
	s_waitcnt lgkmcnt(7)
	v_lshl_add_u32 v36, v36, 10, v250
	global_load_dwordx4 v[36:39], v36, s[98:99]
	s_waitcnt lgkmcnt(6)
	v_lshl_add_u32 v40, v40, 10, v250
	global_load_dwordx4 v[40:43], v40, s[98:99]
	s_waitcnt lgkmcnt(5)
	v_lshl_add_u32 v44, v44, 10, v250
	global_load_dwordx4 v[44:47], v44, s[98:99]
	s_waitcnt lgkmcnt(4)
	v_lshl_add_u32 v48, v48, 10, v250
	global_load_dwordx4 v[48:51], v48, s[98:99]
	s_waitcnt lgkmcnt(3)
	v_lshl_add_u32 v52, v52, 10, v250
	global_load_dwordx4 v[52:55], v52, s[98:99]
	s_waitcnt lgkmcnt(2)
	v_lshl_add_u32 v56, v56, 10, v250
	global_load_dwordx4 v[56:59], v56, s[98:99]
	s_waitcnt lgkmcnt(1)
	v_lshl_add_u32 v60, v60, 10, v250
	global_load_dwordx4 v[60:63], v60, s[98:99]
	s_waitcnt lgkmcnt(0)
	v_lshl_add_u32 v64, v64, 10, v250
	global_load_dwordx4 v[64:67], v64, s[98:99]
	s_branch .LBB0_826

; DI float bflo(u32 u) { return __uint_as_float(u << 16); }
; DI float bfhi(u32 u) { return __uint_as_float(u & 0xffff0000u); }
; DI void dn2_math(const u32x4 (&W)[16], u32x4 x0, u32x4 x1, float* __restrict__ parow, int lane) {
;   f2 xf[8];
; #pragma unroll
;   for (int q = 0; q < 4; ++q) { xf[q] = f2{bflo(x0[q]), bfhi(x0[q])}; xf[4 + q] = f2{bflo(x1[q]), bfhi(x1[q])}; }
;   float pv[16];
; #pragma unroll
;   for (int j = 0; j < 16; ++j) {
;     f2 s2 = {0.f, 0.f};
; #pragma unroll
;     for (int d = 0; d < 4; ++d) {
;       f2 lo = __builtin_amdgcn_cvt_pk_f32_fp8((int)W[j][d], false);
;       f2 hi = __builtin_amdgcn_cvt_pk_f32_fp8((int)W[j][d], true);
;       s2 = lo * xf[2 * d] + s2;
;       s2 = hi * xf[2 * d + 1] + s2;
;     }
;     pv[j] = s2.x + s2.y;
;   }
; DI void peer_down2_phase(const Params& p, unsigned char* smem, int layer, const bf16* __restrict__ x1b, u32* ctr) {
;     ...
;       for (int tl = 0; tl < 16; tl += 2) {
;         dn2_issue(WB, pl + (tl + 1) * 128, wbase, grp);
;         xb_0 = *(const u32x4*)(xb0 + (size_t)(tl + 1) * 1024); xb_1 = *(const u32x4*)(xb0 + (size_t)(tl + 1) * 1024 + 8);
.LBB0_1517:
	ds_read2_b32 v[134:135], v165 offset1:8
	ds_read2_b32 v[126:127], v165 offset0:16 offset1:24
	ds_read2_b32 v[118:119], v165 offset0:32 offset1:40
	ds_read2_b32 v[110:111], v165 offset0:48 offset1:56
	ds_read2_b32 v[102:103], v165 offset0:64 offset1:72
	ds_read2_b32 v[94:95], v165 offset0:80 offset1:88
	ds_read2_b32 v[86:87], v165 offset0:96 offset1:104
	ds_read2_b32 v[78:79], v165 offset0:112 offset1:120
	s_waitcnt lgkmcnt(7)
	v_lshl_add_u32 v130, v135, 10, v250
	v_lshl_add_u32 v134, v134, 10, v250
	global_load_dwordx4 v[134:137], v134, s[98:99]
	global_load_dwordx4 v[130:133], v130, s[98:99]
	s_waitcnt lgkmcnt(6)
	v_lshl_add_u32 v122, v127, 10, v250
	v_lshl_add_u32 v126, v126, 10, v250
	global_load_dwordx4 v[126:129], v126, s[98:99]
	global_load_dwordx4 v[122:125], v122, s[98:99]
	s_waitcnt lgkmcnt(5)
	v_lshl_add_u32 v114, v119, 10, v250
	v_lshl_add_u32 v118, v118, 10, v250
	global_load_dwordx4 v[118:121], v118, s[98:99]
	global_load_dwordx4 v[114:117], v114, s[98:99]
	s_waitcnt lgkmcnt(4)
	v_lshl_add_u32 v106, v111, 10, v250
	v_lshl_add_u32 v110, v110, 10, v250
	global_load_dwordx4 v[110:113], v110, s[98:99]
	global_load_dwordx4 v[106:109], v106, s[98:99]
	s_waitcnt lgkmcnt(3)
	v_lshl_add_u32 v98, v103, 10, v250
	v_lshl_add_u32 v102, v102, 10, v250
	global_load_dwordx4 v[102:105], v102, s[98:99]
	global_load_dwordx4 v[98:101], v98, s[98:99]
	s_waitcnt lgkmcnt(2)
	v_lshl_add_u32 v90, v95, 10, v250
	v_lshl_add_u32 v94, v94, 10, v250
	global_load_dwordx4 v[94:97], v94, s[98:99]
	global_load_dwordx4 v[90:93], v90, s[98:99]
	s_waitcnt lgkmcnt(1)
	v_lshl_add_u32 v82, v87, 10, v250
	v_lshl_add_u32 v86, v86, 10, v250
	global_load_dwordx4 v[86:89], v86, s[98:99]
	global_load_dwordx4 v[82:85], v82, s[98:99]
	s_waitcnt lgkmcnt(0)
	v_lshl_add_u32 v74, v79, 10, v250
	v_lshl_add_u32 v78, v78, 10, v250
	global_load_dwordx4 v[78:81], v78, s[98:99]
	global_load_dwordx4 v[74:77], v74, s[98:99]
	s_nop 0
	global_load_dwordx4 v[138:141], v[198:199], off offset:-2032
	global_load_dwordx4 v[142:145], v[198:199], off offset:-2048
	s_waitcnt vmcnt(35)
	v_cvt_pk_f32_fp8_e32 v[230:231], v2
	v_cvt_pk_f32_fp8_sdwa v[232:233], v2 src0_sel:WORD_1
	v_cvt_pk_f32_fp8_e32 v[234:235], v3
	s_waitcnt vmcnt(18)
	v_lshlrev_b32_e32 v210, 16, v70
	v_and_b32_e32 v211, 0xffff0000, v70
	v_cvt_pk_f32_fp8_sdwa v[236:237], v3 src0_sel:WORD_1
	v_lshlrev_b32_e32 v212, 16, v71
	v_and_b32_e32 v213, 0xffff0000, v71
	v_pk_fma_f32 v[230:231], v[230:231], v[210:211], 0 op_sel_hi:[1,1,0]
	v_lshlrev_b32_e32 v214, 16, v72
	v_and_b32_e32 v215, 0xffff0000, v72
	v_pk_fma_f32 v[230:231], v[232:233], v[212:213], v[230:231]
	v_cvt_pk_f32_fp8_e32 v[232:233], v4
	v_lshlrev_b32_e32 v216, 16, v73
	v_and_b32_e32 v217, 0xffff0000, v73
	v_pk_fma_f32 v[230:231], v[234:235], v[214:215], v[230:231]
	v_cvt_pk_f32_fp8_sdwa v[234:235], v4 src0_sel:WORD_1
	v_pk_fma_f32 v[230:231], v[236:237], v[216:217], v[230:231]
	v_cvt_pk_f32_fp8_e32 v[236:237], v5
	v_lshlrev_b32_e32 v202, 16, v66
	v_and_b32_e32 v203, 0xffff0000, v66
	v_cvt_pk_f32_fp8_sdwa v[238:239], v5 src0_sel:WORD_1
	v_lshlrev_b32_e32 v204, 16, v67
	v_and_b32_e32 v205, 0xffff0000, v67
	v_pk_fma_f32 v[230:231], v[232:233], v[202:203], v[230:231]
	v_lshlrev_b32_e32 v206, 16, v68
	v_and_b32_e32 v207, 0xffff0000, v68
	v_pk_fma_f32 v[230:231], v[234:235], v[204:205], v[230:231]
	v_lshlrev_b32_e32 v208, 16, v69
	v_and_b32_e32 v209, 0xffff0000, v69
	v_pk_fma_f32 v[230:231], v[236:237], v[206:207], v[230:231]
	v_cvt_pk_f32_fp8_sdwa v[232:233], v6 src0_sel:WORD_1
	v_pk_fma_f32 v[230:231], v[238:239], v[208:209], v[230:231]
	v_cvt_pk_f32_fp8_e32 v[234:235], v7
	v_add_f32_e32 v167, v230, v231
	v_cvt_pk_f32_fp8_e32 v[230:231], v6
	v_cvt_pk_f32_fp8_sdwa v[236:237], v7 src0_sel:WORD_1
	v_cvt_pk_f32_fp8_sdwa v[238:239], v9 src0_sel:WORD_1
	v_pk_fma_f32 v[230:231], v[230:231], v[210:211], 0 op_sel_hi:[1,1,0]
	s_nop 0
	v_pk_fma_f32 v[230:231], v[232:233], v[212:213], v[230:231]
	v_cvt_pk_f32_fp8_e32 v[232:233], v8
	v_pk_fma_f32 v[230:231], v[234:235], v[214:215], v[230:231]
	v_cvt_pk_f32_fp8_sdwa v[234:235], v8 src0_sel:WORD_1
	v_pk_fma_f32 v[230:231], v[236:237], v[216:217], v[230:231]
	v_cvt_pk_f32_fp8_e32 v[236:237], v9
	v_pk_fma_f32 v[230:231], v[232:233], v[202:203], v[230:231]
	v_cvt_pk_f32_fp8_sdwa v[232:233], v10 src0_sel:WORD_1
	v_pk_fma_f32 v[230:231], v[234:235], v[204:205], v[230:231]
	v_cvt_pk_f32_fp8_e32 v[234:235], v11
	v_pk_fma_f32 v[230:231], v[236:237], v[206:207], v[230:231]
	v_cvt_pk_f32_fp8_sdwa v[236:237], v11 src0_sel:WORD_1
	v_pk_fma_f32 v[230:231], v[238:239], v[208:209], v[230:231]
	v_cvt_pk_f32_fp8_sdwa v[238:239], v13 src0_sel:WORD_1
	v_add_f32_e32 v169, v230, v231
	v_cvt_pk_f32_fp8_e32 v[230:231], v10
	v_pk_fma_f32 v[230:231], v[230:231], v[210:211], 0 op_sel_hi:[1,1,0]
	s_nop 0
	v_pk_fma_f32 v[230:231], v[232:233], v[212:213], v[230:231]
	v_cvt_pk_f32_fp8_e32 v[232:233], v12
	v_pk_fma_f32 v[230:231], v[234:235], v[214:215], v[230:231]
	v_cvt_pk_f32_fp8_sdwa v[234:235], v12 src0_sel:WORD_1
	v_pk_fma_f32 v[230:231], v[236:237], v[216:217], v[230:231]
	v_cvt_pk_f32_fp8_e32 v[236:237], v13
	v_pk_fma_f32 v[230:231], v[232:233], v[202:203], v[230:231]
	v_cvt_pk_f32_fp8_sdwa v[232:233], v14 src0_sel:WORD_1
	v_pk_fma_f32 v[230:231], v[234:235], v[204:205], v[230:231]
	v_cvt_pk_f32_fp8_e32 v[234:235], v15
	v_pk_fma_f32 v[230:231], v[236:237], v[206:207], v[230:231]
	v_cvt_pk_f32_fp8_sdwa v[236:237], v15 src0_sel:WORD_1
	v_pk_fma_f32 v[230:231], v[238:239], v[208:209], v[230:231]
	v_cvt_pk_f32_fp8_sdwa v[238:239], v17 src0_sel:WORD_1
	v_add_f32_e32 v171, v230, v231
	v_cvt_pk_f32_fp8_e32 v[230:231], v14
; DI void dn2_math(const u32x4 (&W)[16], u32x4 x0, u32x4 x1, float* __restrict__ parow, int lane) {
;     ...
; #pragma unroll
;   for (int j = 0; j < 16; ++j) {
;     f2 s2 = {0.f, 0.f};
; #pragma unroll
;     for (int d = 0; d < 4; ++d) {
;       f2 lo = __builtin_amdgcn_cvt_pk_f32_fp8((int)W[j][d], false);
;       f2 hi = __builtin_amdgcn_cvt_pk_f32_fp8((int)W[j][d], true);
;       s2 = lo * xf[2 * d] + s2;
;       s2 = hi * xf[2 * d + 1] + s2;
;     }
;     pv[j] = s2.x + s2.y;
;   }
	v_pk_fma_f32 v[230:231], v[230:231], v[210:211], 0 op_sel_hi:[1,1,0]
	s_nop 0
	v_pk_fma_f32 v[230:231], v[232:233], v[212:213], v[230:231]
	v_cvt_pk_f32_fp8_e32 v[232:233], v16
	v_pk_fma_f32 v[230:231], v[234:235], v[214:215], v[230:231]
	v_cvt_pk_f32_fp8_sdwa v[234:235], v16 src0_sel:WORD_1
	v_pk_fma_f32 v[230:231], v[236:237], v[216:217], v[230:231]
	v_cvt_pk_f32_fp8_e32 v[236:237], v17
	v_pk_fma_f32 v[230:231], v[232:233], v[202:203], v[230:231]
	v_cvt_pk_f32_fp8_sdwa v[232:233], v18 src0_sel:WORD_1
	v_pk_fma_f32 v[230:231], v[234:235], v[204:205], v[230:231]
	v_cvt_pk_f32_fp8_e32 v[234:235], v19
	v_pk_fma_f32 v[230:231], v[236:237], v[206:207], v[230:231]
	v_cvt_pk_f32_fp8_sdwa v[236:237], v19 src0_sel:WORD_1
	v_pk_fma_f32 v[230:231], v[238:239], v[208:209], v[230:231]
	v_cvt_pk_f32_fp8_sdwa v[238:239], v21 src0_sel:WORD_1
	v_add_f32_e32 v173, v230, v231
	v_cvt_pk_f32_fp8_e32 v[230:231], v18
	v_pk_fma_f32 v[230:231], v[230:231], v[210:211], 0 op_sel_hi:[1,1,0]
	s_nop 0
	v_pk_fma_f32 v[230:231], v[232:233], v[212:213], v[230:231]
	v_cvt_pk_f32_fp8_e32 v[232:233], v20
	v_pk_fma_f32 v[230:231], v[234:235], v[214:215], v[230:231]
	v_cvt_pk_f32_fp8_sdwa v[234:235], v20 src0_sel:WORD_1
	v_pk_fma_f32 v[230:231], v[236:237], v[216:217], v[230:231]
	v_cvt_pk_f32_fp8_e32 v[236:237], v21
	v_pk_fma_f32 v[230:231], v[232:233], v[202:203], v[230:231]
	v_cvt_pk_f32_fp8_sdwa v[232:233], v22 src0_sel:WORD_1
	v_pk_fma_f32 v[230:231], v[234:235], v[204:205], v[230:231]
	v_cvt_pk_f32_fp8_e32 v[234:235], v23
	v_pk_fma_f32 v[230:231], v[236:237], v[206:207], v[230:231]
	v_cvt_pk_f32_fp8_sdwa v[236:237], v23 src0_sel:WORD_1
	v_pk_fma_f32 v[230:231], v[238:239], v[208:209], v[230:231]
	v_cvt_pk_f32_fp8_sdwa v[238:239], v25 src0_sel:WORD_1
	v_add_f32_e32 v175, v230, v231
	v_cvt_pk_f32_fp8_e32 v[230:231], v22
	v_pk_fma_f32 v[230:231], v[230:231], v[210:211], 0 op_sel_hi:[1,1,0]
	s_nop 0
	v_pk_fma_f32 v[230:231], v[232:233], v[212:213], v[230:231]
	v_cvt_pk_f32_fp8_e32 v[232:233], v24
	v_pk_fma_f32 v[230:231], v[234:235], v[214:215], v[230:231]
	v_cvt_pk_f32_fp8_sdwa v[234:235], v24 src0_sel:WORD_1
	v_pk_fma_f32 v[230:231], v[236:237], v[216:217], v[230:231]
	v_cvt_pk_f32_fp8_e32 v[236:237], v25
	v_pk_fma_f32 v[230:231], v[232:233], v[202:203], v[230:231]
	v_cvt_pk_f32_fp8_sdwa v[232:233], v26 src0_sel:WORD_1
	v_pk_fma_f32 v[230:231], v[234:235], v[204:205], v[230:231]
	v_cvt_pk_f32_fp8_e32 v[234:235], v27
	v_pk_fma_f32 v[230:231], v[236:237], v[206:207], v[230:231]
	v_cvt_pk_f32_fp8_sdwa v[236:237], v27 src0_sel:WORD_1
	v_pk_fma_f32 v[230:231], v[238:239], v[208:209], v[230:231]
	v_cvt_pk_f32_fp8_sdwa v[238:239], v29 src0_sel:WORD_1
	v_add_f32_e32 v177, v230, v231
	v_cvt_pk_f32_fp8_e32 v[230:231], v26
	v_pk_fma_f32 v[230:231], v[230:231], v[210:211], 0 op_sel_hi:[1,1,0]
	s_nop 0
	v_pk_fma_f32 v[230:231], v[232:233], v[212:213], v[230:231]
	v_cvt_pk_f32_fp8_e32 v[232:233], v28
	v_pk_fma_f32 v[230:231], v[234:235], v[214:215], v[230:231]
	v_cvt_pk_f32_fp8_sdwa v[234:235], v28 src0_sel:WORD_1
	v_pk_fma_f32 v[230:231], v[236:237], v[216:217], v[230:231]
	v_cvt_pk_f32_fp8_e32 v[236:237], v29
	v_pk_fma_f32 v[230:231], v[232:233], v[202:203], v[230:231]
	v_cvt_pk_f32_fp8_sdwa v[232:233], v30 src0_sel:WORD_1
	v_pk_fma_f32 v[230:231], v[234:235], v[204:205], v[230:231]
	v_cvt_pk_f32_fp8_e32 v[234:235], v31
	v_pk_fma_f32 v[230:231], v[236:237], v[206:207], v[230:231]
	v_cvt_pk_f32_fp8_sdwa v[236:237], v31 src0_sel:WORD_1
	v_pk_fma_f32 v[230:231], v[238:239], v[208:209], v[230:231]
	v_cvt_pk_f32_fp8_sdwa v[238:239], v33 src0_sel:WORD_1
	v_add_f32_e32 v179, v230, v231
	v_cvt_pk_f32_fp8_e32 v[230:231], v30
	v_pk_fma_f32 v[230:231], v[230:231], v[210:211], 0 op_sel_hi:[1,1,0]
	s_nop 0
	v_pk_fma_f32 v[230:231], v[232:233], v[212:213], v[230:231]
	v_cvt_pk_f32_fp8_e32 v[232:233], v32
	v_pk_fma_f32 v[230:231], v[234:235], v[214:215], v[230:231]
	v_cvt_pk_f32_fp8_sdwa v[234:235], v32 src0_sel:WORD_1
	v_pk_fma_f32 v[230:231], v[236:237], v[216:217], v[230:231]
	v_cvt_pk_f32_fp8_e32 v[236:237], v33
	v_pk_fma_f32 v[230:231], v[232:233], v[202:203], v[230:231]
	v_cvt_pk_f32_fp8_sdwa v[232:233], v34 src0_sel:WORD_1
	v_pk_fma_f32 v[230:231], v[234:235], v[204:205], v[230:231]
	v_cvt_pk_f32_fp8_e32 v[234:235], v35
	v_pk_fma_f32 v[230:231], v[236:237], v[206:207], v[230:231]
	v_cvt_pk_f32_fp8_sdwa v[236:237], v35 src0_sel:WORD_1
	v_pk_fma_f32 v[230:231], v[238:239], v[208:209], v[230:231]
	v_cvt_pk_f32_fp8_sdwa v[238:239], v37 src0_sel:WORD_1
	v_add_f32_e32 v181, v230, v231
	v_cvt_pk_f32_fp8_e32 v[230:231], v34
	v_pk_fma_f32 v[230:231], v[230:231], v[210:211], 0 op_sel_hi:[1,1,0]
	s_nop 0
	v_pk_fma_f32 v[230:231], v[232:233], v[212:213], v[230:231]
	v_cvt_pk_f32_fp8_e32 v[232:233], v36
	v_pk_fma_f32 v[230:231], v[234:235], v[214:215], v[230:231]
	v_cvt_pk_f32_fp8_sdwa v[234:235], v36 src0_sel:WORD_1
	v_pk_fma_f32 v[230:231], v[236:237], v[216:217], v[230:231]
	v_cvt_pk_f32_fp8_e32 v[236:237], v37
	v_pk_fma_f32 v[230:231], v[232:233], v[202:203], v[230:231]
	v_cvt_pk_f32_fp8_sdwa v[232:233], v38 src0_sel:WORD_1
	v_pk_fma_f32 v[230:231], v[234:235], v[204:205], v[230:231]
	v_cvt_pk_f32_fp8_e32 v[234:235], v39
	v_pk_fma_f32 v[230:231], v[236:237], v[206:207], v[230:231]
	v_cvt_pk_f32_fp8_sdwa v[236:237], v39 src0_sel:WORD_1
	v_pk_fma_f32 v[230:231], v[238:239], v[208:209], v[230:231]
	v_cvt_pk_f32_fp8_sdwa v[238:239], v41 src0_sel:WORD_1
	v_add_f32_e32 v183, v230, v231
	v_cvt_pk_f32_fp8_e32 v[230:231], v38
	v_pk_fma_f32 v[230:231], v[230:231], v[210:211], 0 op_sel_hi:[1,1,0]
	s_nop 0
	v_pk_fma_f32 v[230:231], v[232:233], v[212:213], v[230:231]
	v_cvt_pk_f32_fp8_e32 v[232:233], v40
; DI void dn2_math(const u32x4 (&W)[16], u32x4 x0, u32x4 x1, float* __restrict__ parow, int lane) {
;     ...
; #pragma unroll
;   for (int j = 0; j < 16; ++j) {
;     f2 s2 = {0.f, 0.f};
; #pragma unroll
;     for (int d = 0; d < 4; ++d) {
;       f2 lo = __builtin_amdgcn_cvt_pk_f32_fp8((int)W[j][d], false);
;       f2 hi = __builtin_amdgcn_cvt_pk_f32_fp8((int)W[j][d], true);
;       s2 = lo * xf[2 * d] + s2;
;       s2 = hi * xf[2 * d + 1] + s2;
;     }
;     pv[j] = s2.x + s2.y;
;   }
	v_pk_fma_f32 v[230:231], v[234:235], v[214:215], v[230:231]
	v_cvt_pk_f32_fp8_sdwa v[234:235], v40 src0_sel:WORD_1
	v_pk_fma_f32 v[230:231], v[236:237], v[216:217], v[230:231]
	v_cvt_pk_f32_fp8_e32 v[236:237], v41
	v_pk_fma_f32 v[230:231], v[232:233], v[202:203], v[230:231]
	v_cvt_pk_f32_fp8_sdwa v[232:233], v42 src0_sel:WORD_1
	v_pk_fma_f32 v[230:231], v[234:235], v[204:205], v[230:231]
	v_cvt_pk_f32_fp8_e32 v[234:235], v43
	v_pk_fma_f32 v[230:231], v[236:237], v[206:207], v[230:231]
	v_cvt_pk_f32_fp8_sdwa v[236:237], v43 src0_sel:WORD_1
	v_pk_fma_f32 v[230:231], v[238:239], v[208:209], v[230:231]
	v_cvt_pk_f32_fp8_sdwa v[238:239], v45 src0_sel:WORD_1
	v_add_f32_e32 v185, v230, v231
	v_cvt_pk_f32_fp8_e32 v[230:231], v42
	v_pk_fma_f32 v[230:231], v[230:231], v[210:211], 0 op_sel_hi:[1,1,0]
	s_nop 0
	v_pk_fma_f32 v[230:231], v[232:233], v[212:213], v[230:231]
	v_cvt_pk_f32_fp8_e32 v[232:233], v44
	v_pk_fma_f32 v[230:231], v[234:235], v[214:215], v[230:231]
	v_cvt_pk_f32_fp8_sdwa v[234:235], v44 src0_sel:WORD_1
	v_pk_fma_f32 v[230:231], v[236:237], v[216:217], v[230:231]
	v_cvt_pk_f32_fp8_e32 v[236:237], v45
	v_pk_fma_f32 v[230:231], v[232:233], v[202:203], v[230:231]
	v_cvt_pk_f32_fp8_sdwa v[232:233], v46 src0_sel:WORD_1
	v_pk_fma_f32 v[230:231], v[234:235], v[204:205], v[230:231]
	v_cvt_pk_f32_fp8_e32 v[234:235], v47
	v_pk_fma_f32 v[230:231], v[236:237], v[206:207], v[230:231]
	v_cvt_pk_f32_fp8_sdwa v[236:237], v47 src0_sel:WORD_1
	v_pk_fma_f32 v[230:231], v[238:239], v[208:209], v[230:231]
	v_cvt_pk_f32_fp8_sdwa v[238:239], v49 src0_sel:WORD_1
	v_add_f32_e32 v187, v230, v231
	v_cvt_pk_f32_fp8_e32 v[230:231], v46
	v_pk_fma_f32 v[230:231], v[230:231], v[210:211], 0 op_sel_hi:[1,1,0]
	s_nop 0
	v_pk_fma_f32 v[230:231], v[232:233], v[212:213], v[230:231]
	v_cvt_pk_f32_fp8_e32 v[232:233], v48
	v_pk_fma_f32 v[230:231], v[234:235], v[214:215], v[230:231]
	v_cvt_pk_f32_fp8_sdwa v[234:235], v48 src0_sel:WORD_1
	v_pk_fma_f32 v[230:231], v[236:237], v[216:217], v[230:231]
	v_cvt_pk_f32_fp8_e32 v[236:237], v49
	v_pk_fma_f32 v[230:231], v[232:233], v[202:203], v[230:231]
	v_cvt_pk_f32_fp8_sdwa v[232:233], v50 src0_sel:WORD_1
	v_pk_fma_f32 v[230:231], v[234:235], v[204:205], v[230:231]
	v_cvt_pk_f32_fp8_e32 v[234:235], v51
	v_pk_fma_f32 v[230:231], v[236:237], v[206:207], v[230:231]
	v_cvt_pk_f32_fp8_sdwa v[236:237], v51 src0_sel:WORD_1
	v_pk_fma_f32 v[230:231], v[238:239], v[208:209], v[230:231]
	v_cvt_pk_f32_fp8_sdwa v[238:239], v53 src0_sel:WORD_1
	v_add_f32_e32 v189, v230, v231
	v_cvt_pk_f32_fp8_e32 v[230:231], v50
	v_pk_fma_f32 v[230:231], v[230:231], v[210:211], 0 op_sel_hi:[1,1,0]
	s_nop 0
	v_pk_fma_f32 v[230:231], v[232:233], v[212:213], v[230:231]
	v_cvt_pk_f32_fp8_e32 v[232:233], v52
	v_pk_fma_f32 v[230:231], v[234:235], v[214:215], v[230:231]
	v_cvt_pk_f32_fp8_sdwa v[234:235], v52 src0_sel:WORD_1
	v_pk_fma_f32 v[230:231], v[236:237], v[216:217], v[230:231]
	v_cvt_pk_f32_fp8_e32 v[236:237], v53
	v_pk_fma_f32 v[230:231], v[232:233], v[202:203], v[230:231]
	v_cvt_pk_f32_fp8_sdwa v[232:233], v54 src0_sel:WORD_1
	v_pk_fma_f32 v[230:231], v[234:235], v[204:205], v[230:231]
	v_cvt_pk_f32_fp8_e32 v[234:235], v55
	v_pk_fma_f32 v[230:231], v[236:237], v[206:207], v[230:231]
	v_cvt_pk_f32_fp8_sdwa v[236:237], v55 src0_sel:WORD_1
	v_pk_fma_f32 v[230:231], v[238:239], v[208:209], v[230:231]
	v_cvt_pk_f32_fp8_sdwa v[238:239], v57 src0_sel:WORD_1
	v_add_f32_e32 v229, v230, v231
	v_cvt_pk_f32_fp8_e32 v[230:231], v54
	v_pk_fma_f32 v[230:231], v[230:231], v[210:211], 0 op_sel_hi:[1,1,0]
	s_nop 0
	v_pk_fma_f32 v[230:231], v[232:233], v[212:213], v[230:231]
	v_cvt_pk_f32_fp8_e32 v[232:233], v56
	v_pk_fma_f32 v[230:231], v[234:235], v[214:215], v[230:231]
	v_cvt_pk_f32_fp8_sdwa v[234:235], v56 src0_sel:WORD_1
	v_pk_fma_f32 v[230:231], v[236:237], v[216:217], v[230:231]
	v_cvt_pk_f32_fp8_e32 v[236:237], v57
	v_pk_fma_f32 v[230:231], v[232:233], v[202:203], v[230:231]
	v_cvt_pk_f32_fp8_sdwa v[232:233], v58 src0_sel:WORD_1
	v_pk_fma_f32 v[230:231], v[234:235], v[204:205], v[230:231]
	v_cvt_pk_f32_fp8_e32 v[234:235], v59
	v_pk_fma_f32 v[230:231], v[236:237], v[206:207], v[230:231]
	v_cvt_pk_f32_fp8_sdwa v[236:237], v59 src0_sel:WORD_1
	v_pk_fma_f32 v[230:231], v[238:239], v[208:209], v[230:231]
	v_cvt_pk_f32_fp8_sdwa v[238:239], v61 src0_sel:WORD_1
	v_add_f32_e32 v240, v230, v231
	v_cvt_pk_f32_fp8_e32 v[230:231], v58
	v_pk_fma_f32 v[230:231], v[230:231], v[210:211], 0 op_sel_hi:[1,1,0]
	s_nop 0
	v_pk_fma_f32 v[230:231], v[232:233], v[212:213], v[230:231]
	v_cvt_pk_f32_fp8_e32 v[232:233], v60
	v_pk_fma_f32 v[230:231], v[234:235], v[214:215], v[230:231]
	v_cvt_pk_f32_fp8_sdwa v[234:235], v60 src0_sel:WORD_1
	v_pk_fma_f32 v[230:231], v[236:237], v[216:217], v[230:231]
	v_cvt_pk_f32_fp8_e32 v[236:237], v61
	v_pk_fma_f32 v[230:231], v[232:233], v[202:203], v[230:231]
	v_cvt_pk_f32_fp8_sdwa v[232:233], v62 src0_sel:WORD_1
	v_pk_fma_f32 v[230:231], v[234:235], v[204:205], v[230:231]
	v_cvt_pk_f32_fp8_e32 v[234:235], v63
	v_pk_fma_f32 v[230:231], v[236:237], v[206:207], v[230:231]
	v_cvt_pk_f32_fp8_sdwa v[236:237], v63 src0_sel:WORD_1
	v_pk_fma_f32 v[230:231], v[238:239], v[208:209], v[230:231]
	s_nop 0
	v_add_f32_e32 v238, v230, v231
	v_cvt_pk_f32_fp8_e32 v[230:231], v62
; DI void dn2_math(const u32x4 (&W)[16], u32x4 x0, u32x4 x1, float* __restrict__ parow, int lane) {
;     ...
;   const bool b2 = lane & 4, b1 = lane & 2, b0 = lane & 1;
;   float q8[8];
; #pragma unroll
;   for (int i = 0; i < 8; ++i) { float snd = b2 ? pv[i] : pv[i + 8]; float kp = b2 ? pv[i + 8] : pv[i]; q8[i] = kp + __shfl_xor(snd, 4); }
;   float q4[4];
; #pragma unroll
;   for (int i = 0; i < 4; ++i) { float snd = b1 ? q8[i] : q8[i + 4]; float kp = b1 ? q8[i + 4] : q8[i]; q4[i] = kp + __shfl_xor(snd, 2); }
;   float r2[2];
; #pragma unroll
;   for (int i = 0; i < 2; ++i) { float snd = b0 ? q4[i] : q4[i + 2]; float kp = b0 ? q4[i + 2] : q4[i]; r2[i] = kp + __shfl_xor(snd, 1); }
;   const int j0 = (b0 ? 2 : 0) + (b1 ? 4 : 0) + (b2 ? 8 : 0);
;   const int grp = lane >> 3;
;   parow[8 * j0 + grp] = r2[0];
;   parow[8 * (j0 + 1) + grp] = r2[1];
; }
; DI void peer_down2_phase(const Params& p, unsigned char* smem, int layer, const bf16* __restrict__ x1b, u32* ctr) {
;     ...
;         if (tl + 2 < 16) {
;           dn2_issue(WA, pl + (tl + 2) * 128, wbase, grp);
;           xa0 = *(const u32x4*)(xb0 + (size_t)(tl + 2) * 1024); xa1 = *(const u32x4*)(xb0 + (size_t)(tl + 2) * 1024 + 8);
;         }
	v_pk_fma_f32 v[210:211], v[230:231], v[210:211], 0 op_sel_hi:[1,1,0]
	s_nop 0
	v_pk_fma_f32 v[210:211], v[232:233], v[212:213], v[210:211]
	v_cvt_pk_f32_fp8_e32 v[212:213], v64
	v_pk_fma_f32 v[210:211], v[234:235], v[214:215], v[210:211]
	v_cvt_pk_f32_fp8_sdwa v[214:215], v64 src0_sel:WORD_1
	v_pk_fma_f32 v[210:211], v[236:237], v[216:217], v[210:211]
	v_cvt_pk_f32_fp8_e32 v[216:217], v65
	v_cvt_pk_f32_fp8_sdwa v[230:231], v65 src0_sel:WORD_1
	v_pk_fma_f32 v[202:203], v[212:213], v[202:203], v[210:211]
	s_nop 0
	v_pk_fma_f32 v[202:203], v[214:215], v[204:205], v[202:203]
	v_pk_fma_f32 v[202:203], v[216:217], v[206:207], v[202:203]
	v_pk_fma_f32 v[202:203], v[230:231], v[208:209], v[202:203]
	v_add_f32_e32 v202, v202, v203
	s_nop 1
	v_add_f32_dpp v167, v167, v167 row_shl:4 row_mask:0xf bank_mask:0x5
	v_add_f32_dpp v173, v173, v173 row_shl:4 row_mask:0xf bank_mask:0x5
	v_add_f32_dpp v175, v175, v175 row_shl:4 row_mask:0xf bank_mask:0x5
	v_add_f32_dpp v169, v169, v169 row_shl:4 row_mask:0xf bank_mask:0x5
	v_add_f32_dpp v171, v171, v171 row_shl:4 row_mask:0xf bank_mask:0x5
	v_add_f32_dpp v177, v177, v177 row_shl:4 row_mask:0xf bank_mask:0x5
	v_add_f32_dpp v179, v179, v179 row_shl:4 row_mask:0xf bank_mask:0x5
	v_add_f32_dpp v181, v181, v181 row_shl:4 row_mask:0xf bank_mask:0x5
	v_add_f32_dpp v167, v183, v183 row_shr:4 row_mask:0xf bank_mask:0xa
	v_add_f32_dpp v173, v189, v189 row_shr:4 row_mask:0xf bank_mask:0xa
	v_add_f32_dpp v175, v229, v229 row_shr:4 row_mask:0xf bank_mask:0xa
	v_add_f32_dpp v169, v185, v185 row_shr:4 row_mask:0xf bank_mask:0xa
	v_add_f32_dpp v171, v187, v187 row_shr:4 row_mask:0xf bank_mask:0xa
	v_add_f32_dpp v177, v240, v240 row_shr:4 row_mask:0xf bank_mask:0xa
	v_add_f32_dpp v179, v238, v238 row_shr:4 row_mask:0xf bank_mask:0xa
	v_add_f32_dpp v181, v202, v202 row_shr:4 row_mask:0xf bank_mask:0xa
	s_nop 1
	v_add_f32_dpp v167, v167, v167 quad_perm:[2,3,0,1] row_mask:0xf bank_mask:0xf
	v_add_f32_dpp v171, v171, v171 quad_perm:[2,3,0,1] row_mask:0xf bank_mask:0xf
	v_add_f32_dpp v169, v169, v169 quad_perm:[2,3,0,1] row_mask:0xf bank_mask:0xf
	v_add_f32_dpp v173, v173, v173 quad_perm:[2,3,0,1] row_mask:0xf bank_mask:0xf
	v_add_f32_dpp v175, v175, v175 quad_perm:[2,3,0,1] row_mask:0xf bank_mask:0xf
	v_add_f32_dpp v179, v179, v179 quad_perm:[2,3,0,1] row_mask:0xf bank_mask:0xf
	v_add_f32_dpp v177, v177, v177 quad_perm:[2,3,0,1] row_mask:0xf bank_mask:0xf
	v_add_f32_dpp v181, v181, v181 quad_perm:[2,3,0,1] row_mask:0xf bank_mask:0xf
	v_cndmask_b32_e64 v167, v175, v167, s[10:11]
	v_cndmask_b32_e64 v171, v179, v171, s[10:11]
	v_cndmask_b32_e64 v169, v177, v169, s[10:11]
	v_cndmask_b32_e64 v173, v181, v173, s[10:11]
	s_nop 1
	v_add_f32_dpp v167, v167, v167 quad_perm:[1,0,3,2] row_mask:0xf bank_mask:0xf
	v_add_f32_dpp v169, v169, v169 quad_perm:[1,0,3,2] row_mask:0xf bank_mask:0xf
	v_add_f32_dpp v171, v171, v171 quad_perm:[1,0,3,2] row_mask:0xf bank_mask:0xf
	v_add_f32_dpp v173, v173, v173 quad_perm:[1,0,3,2] row_mask:0xf bank_mask:0xf
	v_cndmask_b32_e64 v167, v171, v167, s[12:13]
	v_cndmask_b32_e64 v169, v173, v169, s[12:13]
	global_store_dword v[200:201], v167, off offset:-512
	global_store_dword v[200:201], v169, off offset:-480
	s_cmp_gt_u32 s40, 13
	s_cselect_b64 s[28:29], -1, 0
	s_cbranch_scc1 .LBB0_1516
	ds_read2_b32 v[2:3], v165 offset0:128 offset1:136
	ds_read2_b32 v[10:11], v165 offset0:144 offset1:152
	ds_read2_b32 v[18:19], v165 offset0:160 offset1:168
	ds_read2_b32 v[26:27], v165 offset0:176 offset1:184
	ds_read2_b32 v[34:35], v165 offset0:192 offset1:200
	ds_read2_b32 v[42:43], v165 offset0:208 offset1:216
	ds_read2_b32 v[50:51], v165 offset0:224 offset1:232
	ds_read2_b32 v[58:59], v165 offset0:240 offset1:248
	s_waitcnt lgkmcnt(7)
	v_lshl_add_u32 v6, v3, 10, v250
	v_lshl_add_u32 v2, v2, 10, v250
	global_load_dwordx4 v[2:5], v2, s[98:99]
	global_load_dwordx4 v[6:9], v6, s[98:99]
	s_waitcnt lgkmcnt(6)
	v_lshl_add_u32 v14, v11, 10, v250
	v_lshl_add_u32 v10, v10, 10, v250
	global_load_dwordx4 v[10:13], v10, s[98:99]
	global_load_dwordx4 v[14:17], v14, s[98:99]
	s_waitcnt lgkmcnt(5)
	v_lshl_add_u32 v22, v19, 10, v250
	v_lshl_add_u32 v18, v18, 10, v250
	global_load_dwordx4 v[18:21], v18, s[98:99]
	global_load_dwordx4 v[22:25], v22, s[98:99]
	s_waitcnt lgkmcnt(4)
	v_lshl_add_u32 v30, v27, 10, v250
	v_lshl_add_u32 v26, v26, 10, v250
	global_load_dwordx4 v[26:29], v26, s[98:99]
	global_load_dwordx4 v[30:33], v30, s[98:99]
	s_waitcnt lgkmcnt(3)
	v_lshl_add_u32 v38, v35, 10, v250
	v_lshl_add_u32 v34, v34, 10, v250
	global_load_dwordx4 v[34:37], v34, s[98:99]
	global_load_dwordx4 v[38:41], v38, s[98:99]
	s_waitcnt lgkmcnt(2)
	v_lshl_add_u32 v46, v43, 10, v250
	v_lshl_add_u32 v42, v42, 10, v250
	global_load_dwordx4 v[42:45], v42, s[98:99]
	global_load_dwordx4 v[46:49], v46, s[98:99]
	s_waitcnt lgkmcnt(1)
	v_lshl_add_u32 v54, v51, 10, v250
	v_lshl_add_u32 v50, v50, 10, v250
	global_load_dwordx4 v[50:53], v50, s[98:99]
	global_load_dwordx4 v[54:57], v54, s[98:99]
	s_waitcnt lgkmcnt(0)
	v_lshl_add_u32 v62, v59, 10, v250
	v_lshl_add_u32 v58, v58, 10, v250
	global_load_dwordx4 v[58:61], v58, s[98:99]
	global_load_dwordx4 v[62:65], v62, s[98:99]
	s_nop 0
	global_load_dwordx4 v[66:69], v[198:199], off offset:16
	global_load_dwordx4 v[70:73], v[198:199], off
	s_branch .LBB0_1516

; DI void up_issue(u32x4 (&W)[16], u32 (&pj)[16], const u32* pl, const unsigned char* wbase, int grp) {
; #pragma unroll
;   for (int j = 0; j < 16; ++j) {
;     pj[j] = pl[8 * j + grp];
;     W[j] = *(const u32x4*)(wbase + (size_t)(pj[j] >> 16) * 1024);
;   }
; }
; DI void up_math(const u32x4 (&W)[16], const u32 (&pj)[16], float* __restrict__ yrow, int lane) {
;   f2 y[8];
; #pragma unroll
;   for (int i = 0; i < 8; ++i) y[i] = f2{0.f, 0.f};
; #pragma unroll
;   for (int j = 0; j < 16; ++j) {
;     const float h = __uint_as_float(pj[j] << 16);
;     const f2 hh = {h, h};
; #pragma unroll
;     for (int d = 0; d < 4; ++d) {
;       f2 lo = __builtin_amdgcn_cvt_pk_f32_fp8((int)W[j][d], false);
;       f2 hi = __builtin_amdgcn_cvt_pk_f32_fp8((int)W[j][d], true);
;       y[2 * d] = lo * hh + y[2 * d];
;       y[2 * d + 1] = hi * hh + y[2 * d + 1];
;     }
;   }
; DI void peer_up_phase(const Params& p, unsigned char* smem, int layer, u32* ctr) {
;     ...
;       for (int tl = 0; tl < 16; tl += 2) {
;         up_issue(WB, pB, pl + (tl + 1) * 128, wbase, grp);
;         __builtin_amdgcn_sched_barrier(0);
;         up_math(WA, pA, ybase + (size_t)tl * 1024, lane);
.LBB0_1650:
	v_mov_b32_e32 v210, 0
	v_mov_b32_e32 v211, 0
	v_mov_b32_e32 v208, 0
	v_mov_b32_e32 v209, 0
	v_mov_b32_e32 v206, 0
	v_mov_b32_e32 v207, 0
	ds_read_u16_d16_hi v210, v145
	ds_read_u16_d16_hi v211, v145 offset:32
	ds_read_u16_d16_hi v208, v145 offset:64
	ds_read_u16_d16_hi v209, v145 offset:96
	ds_read_u16_d16_hi v206, v145 offset:128
	ds_read_u16_d16_hi v207, v145 offset:160
	ds_read_u16_d16_hi v204, v145 offset:192
	ds_read_u16_d16_hi v205, v145 offset:224
	ds_read_u16_d16_hi v202, v145 offset:256
	ds_read_u16_d16_hi v203, v145 offset:288
	ds_read_u16_d16_hi v200, v145 offset:320
	ds_read_u16_d16_hi v201, v145 offset:352
	ds_read_u16_d16_hi v198, v145 offset:384
	ds_read_u16_d16_hi v199, v145 offset:416
	ds_read_u16_d16_hi v196, v145 offset:448
	ds_read_u16_d16_hi v197, v145 offset:480
	ds_read_u16 v128, v145 offset:2
	ds_read_u16 v124, v145 offset:34
	ds_read_u16 v120, v145 offset:66
	ds_read_u16 v116, v145 offset:98
	ds_read_u16 v112, v145 offset:130
	ds_read_u16 v108, v145 offset:162
	ds_read_u16 v104, v145 offset:194
	ds_read_u16 v100, v145 offset:226
	ds_read_u16 v96, v145 offset:258
	ds_read_u16 v92, v145 offset:290
	ds_read_u16 v88, v145 offset:322
	ds_read_u16 v84, v145 offset:354
	ds_read_u16 v80, v145 offset:386
	ds_read_u16 v76, v145 offset:418
	ds_read_u16 v72, v145 offset:450
	ds_read_u16 v68, v145 offset:482
	s_waitcnt lgkmcnt(15)
	v_lshl_add_u32 v128, v128, 10, v250
	global_load_dwordx4 v[128:131], v128, s[98:99]
	s_waitcnt lgkmcnt(14)
	v_lshl_add_u32 v124, v124, 10, v250
	global_load_dwordx4 v[124:127], v124, s[98:99]
	s_waitcnt lgkmcnt(13)
	v_lshl_add_u32 v120, v120, 10, v250
	global_load_dwordx4 v[120:123], v120, s[98:99]
	s_waitcnt lgkmcnt(12)
	v_lshl_add_u32 v116, v116, 10, v250
	global_load_dwordx4 v[116:119], v116, s[98:99]
	s_waitcnt lgkmcnt(11)
	v_lshl_add_u32 v112, v112, 10, v250
	global_load_dwordx4 v[112:115], v112, s[98:99]
	s_waitcnt lgkmcnt(10)
	v_lshl_add_u32 v108, v108, 10, v250
	global_load_dwordx4 v[108:111], v108, s[98:99]
	s_waitcnt lgkmcnt(9)
	v_lshl_add_u32 v104, v104, 10, v250
	global_load_dwordx4 v[104:107], v104, s[98:99]
	s_waitcnt lgkmcnt(8)
	v_lshl_add_u32 v100, v100, 10, v250
	global_load_dwordx4 v[100:103], v100, s[98:99]
	s_waitcnt lgkmcnt(7)
	v_lshl_add_u32 v96, v96, 10, v250
	global_load_dwordx4 v[96:99], v96, s[98:99]
	s_waitcnt lgkmcnt(6)
	v_lshl_add_u32 v92, v92, 10, v250
	global_load_dwordx4 v[92:95], v92, s[98:99]
	s_waitcnt lgkmcnt(5)
	v_lshl_add_u32 v88, v88, 10, v250
	global_load_dwordx4 v[88:91], v88, s[98:99]
	s_waitcnt lgkmcnt(4)
	v_lshl_add_u32 v84, v84, 10, v250
	global_load_dwordx4 v[84:87], v84, s[98:99]
	s_waitcnt lgkmcnt(3)
	v_lshl_add_u32 v80, v80, 10, v250
	global_load_dwordx4 v[80:83], v80, s[98:99]
	s_waitcnt lgkmcnt(2)
	v_lshl_add_u32 v76, v76, 10, v250
	global_load_dwordx4 v[76:79], v76, s[98:99]
	s_waitcnt lgkmcnt(1)
	v_lshl_add_u32 v72, v72, 10, v250
	global_load_dwordx4 v[72:75], v72, s[98:99]
	s_waitcnt lgkmcnt(0)
	v_lshl_add_u32 v68, v68, 10, v250
	global_load_dwordx4 v[68:71], v68, s[98:99]
	s_waitcnt vmcnt(31)
	v_cvt_pk_f32_fp8_e32 v[216:217], v4
	v_cvt_pk_f32_fp8_sdwa v[226:227], v4 src0_sel:WORD_1
	v_cvt_pk_f32_fp8_e32 v[228:229], v5
	v_cvt_pk_f32_fp8_sdwa v[230:231], v5 src0_sel:WORD_1
	v_cvt_pk_f32_fp8_e32 v[232:233], v6
	v_cvt_pk_f32_fp8_sdwa v[234:235], v6 src0_sel:WORD_1
	v_cvt_pk_f32_fp8_e32 v[236:237], v7
	v_cvt_pk_f32_fp8_sdwa v[238:239], v7 src0_sel:WORD_1
	s_waitcnt vmcnt(30)
	v_cvt_pk_f32_fp8_e32 v[240:241], v8
	v_cvt_pk_f32_fp8_sdwa v[242:243], v8 src0_sel:WORD_1
	v_cvt_pk_f32_fp8_e32 v[244:245], v9
	v_cvt_pk_f32_fp8_sdwa v[246:247], v9 src0_sel:WORD_1
	v_pk_fma_f32 v[216:217], v[178:179], v[216:217], 0 op_sel_hi:[0,1,0]
	v_pk_fma_f32 v[226:227], v[178:179], v[226:227], 0 op_sel_hi:[0,1,0]
	v_pk_fma_f32 v[228:229], v[178:179], v[228:229], 0 op_sel_hi:[0,1,0]
	v_pk_fma_f32 v[230:231], v[178:179], v[230:231], 0 op_sel_hi:[0,1,0]
	v_pk_fma_f32 v[232:233], v[178:179], v[232:233], 0 op_sel_hi:[0,1,0]
	v_pk_fma_f32 v[234:235], v[178:179], v[234:235], 0 op_sel_hi:[0,1,0]
	v_pk_fma_f32 v[236:237], v[178:179], v[236:237], 0 op_sel_hi:[0,1,0]
	v_pk_fma_f32 v[238:239], v[178:179], v[238:239], 0 op_sel_hi:[0,1,0]
	v_pk_fma_f32 v[216:217], v[178:179], v[240:241], v[216:217] op_sel:[1,0,0] op_sel_hi:[1,1,1]
	v_cvt_pk_f32_fp8_e32 v[240:241], v10
	v_pk_fma_f32 v[226:227], v[178:179], v[242:243], v[226:227] op_sel:[1,0,0] op_sel_hi:[1,1,1]
	v_pk_fma_f32 v[228:229], v[178:179], v[244:245], v[228:229] op_sel:[1,0,0] op_sel_hi:[1,1,1]
	v_pk_fma_f32 v[230:231], v[178:179], v[246:247], v[230:231] op_sel:[1,0,0] op_sel_hi:[1,1,1]
	v_cvt_pk_f32_fp8_sdwa v[242:243], v10 src0_sel:WORD_1
	v_cvt_pk_f32_fp8_e32 v[244:245], v11
	v_cvt_pk_f32_fp8_sdwa v[246:247], v11 src0_sel:WORD_1
	v_pk_fma_f32 v[232:233], v[178:179], v[240:241], v[232:233] op_sel:[1,0,0] op_sel_hi:[1,1,1]
	s_waitcnt vmcnt(29)
	v_cvt_pk_f32_fp8_e32 v[240:241], v12
	v_pk_fma_f32 v[234:235], v[178:179], v[242:243], v[234:235] op_sel:[1,0,0] op_sel_hi:[1,1,1]
	v_pk_fma_f32 v[236:237], v[178:179], v[244:245], v[236:237] op_sel:[1,0,0] op_sel_hi:[1,1,1]
	v_pk_fma_f32 v[238:239], v[178:179], v[246:247], v[238:239] op_sel:[1,0,0] op_sel_hi:[1,1,1]
	v_cvt_pk_f32_fp8_sdwa v[242:243], v12 src0_sel:WORD_1
	v_cvt_pk_f32_fp8_e32 v[244:245], v13
	v_cvt_pk_f32_fp8_sdwa v[246:247], v13 src0_sel:WORD_1
	v_pk_fma_f32 v[216:217], v[180:181], v[240:241], v[216:217] op_sel_hi:[0,1,1]
	v_cvt_pk_f32_fp8_e32 v[240:241], v14
	v_pk_fma_f32 v[226:227], v[180:181], v[242:243], v[226:227] op_sel_hi:[0,1,1]
	v_pk_fma_f32 v[228:229], v[180:181], v[244:245], v[228:229] op_sel_hi:[0,1,1]
	v_pk_fma_f32 v[230:231], v[180:181], v[246:247], v[230:231] op_sel_hi:[0,1,1]
	v_cvt_pk_f32_fp8_sdwa v[242:243], v14 src0_sel:WORD_1
	v_cvt_pk_f32_fp8_e32 v[244:245], v15
	v_cvt_pk_f32_fp8_sdwa v[246:247], v15 src0_sel:WORD_1
	v_pk_fma_f32 v[232:233], v[180:181], v[240:241], v[232:233] op_sel_hi:[0,1,1]
	s_waitcnt vmcnt(28)
; DI void up_math(const u32x4 (&W)[16], const u32 (&pj)[16], float* __restrict__ yrow, int lane) {
;     ...
; #pragma unroll
;   for (int j = 0; j < 16; ++j) {
;     const float h = __uint_as_float(pj[j] << 16);
;     const f2 hh = {h, h};
; #pragma unroll
;     for (int d = 0; d < 4; ++d) {
;       f2 lo = __builtin_amdgcn_cvt_pk_f32_fp8((int)W[j][d], false);
;       f2 hi = __builtin_amdgcn_cvt_pk_f32_fp8((int)W[j][d], true);
;       y[2 * d] = lo * hh + y[2 * d];
;       y[2 * d + 1] = hi * hh + y[2 * d + 1];
;     }
;   }
	v_cvt_pk_f32_fp8_e32 v[240:241], v16
	v_pk_fma_f32 v[234:235], v[180:181], v[242:243], v[234:235] op_sel_hi:[0,1,1]
	v_pk_fma_f32 v[236:237], v[180:181], v[244:245], v[236:237] op_sel_hi:[0,1,1]
	v_pk_fma_f32 v[238:239], v[180:181], v[246:247], v[238:239] op_sel_hi:[0,1,1]
	v_cvt_pk_f32_fp8_sdwa v[242:243], v16 src0_sel:WORD_1
	v_cvt_pk_f32_fp8_e32 v[244:245], v17
	v_cvt_pk_f32_fp8_sdwa v[246:247], v17 src0_sel:WORD_1
	v_pk_fma_f32 v[216:217], v[180:181], v[240:241], v[216:217] op_sel:[1,0,0] op_sel_hi:[1,1,1]
	v_cvt_pk_f32_fp8_e32 v[240:241], v18
	v_pk_fma_f32 v[226:227], v[180:181], v[242:243], v[226:227] op_sel:[1,0,0] op_sel_hi:[1,1,1]
	v_pk_fma_f32 v[228:229], v[180:181], v[244:245], v[228:229] op_sel:[1,0,0] op_sel_hi:[1,1,1]
	v_pk_fma_f32 v[230:231], v[180:181], v[246:247], v[230:231] op_sel:[1,0,0] op_sel_hi:[1,1,1]
	v_cvt_pk_f32_fp8_sdwa v[242:243], v18 src0_sel:WORD_1
	v_cvt_pk_f32_fp8_e32 v[244:245], v19
	v_cvt_pk_f32_fp8_sdwa v[246:247], v19 src0_sel:WORD_1
	v_pk_fma_f32 v[232:233], v[180:181], v[240:241], v[232:233] op_sel:[1,0,0] op_sel_hi:[1,1,1]
	s_waitcnt vmcnt(27)
	v_cvt_pk_f32_fp8_e32 v[240:241], v20
	v_pk_fma_f32 v[234:235], v[180:181], v[242:243], v[234:235] op_sel:[1,0,0] op_sel_hi:[1,1,1]
	v_pk_fma_f32 v[236:237], v[180:181], v[244:245], v[236:237] op_sel:[1,0,0] op_sel_hi:[1,1,1]
	v_pk_fma_f32 v[238:239], v[180:181], v[246:247], v[238:239] op_sel:[1,0,0] op_sel_hi:[1,1,1]
	v_cvt_pk_f32_fp8_sdwa v[242:243], v20 src0_sel:WORD_1
	v_cvt_pk_f32_fp8_e32 v[244:245], v21
	v_cvt_pk_f32_fp8_sdwa v[246:247], v21 src0_sel:WORD_1
	v_pk_fma_f32 v[216:217], v[182:183], v[240:241], v[216:217] op_sel_hi:[0,1,1]
	v_cvt_pk_f32_fp8_e32 v[240:241], v22
	v_pk_fma_f32 v[226:227], v[182:183], v[242:243], v[226:227] op_sel_hi:[0,1,1]
	v_pk_fma_f32 v[228:229], v[182:183], v[244:245], v[228:229] op_sel_hi:[0,1,1]
	v_pk_fma_f32 v[230:231], v[182:183], v[246:247], v[230:231] op_sel_hi:[0,1,1]
	v_cvt_pk_f32_fp8_sdwa v[242:243], v22 src0_sel:WORD_1
	v_cvt_pk_f32_fp8_e32 v[244:245], v23
	v_cvt_pk_f32_fp8_sdwa v[246:247], v23 src0_sel:WORD_1
	v_pk_fma_f32 v[232:233], v[182:183], v[240:241], v[232:233] op_sel_hi:[0,1,1]
	s_waitcnt vmcnt(26)
	v_cvt_pk_f32_fp8_e32 v[240:241], v24
	v_pk_fma_f32 v[234:235], v[182:183], v[242:243], v[234:235] op_sel_hi:[0,1,1]
	v_pk_fma_f32 v[236:237], v[182:183], v[244:245], v[236:237] op_sel_hi:[0,1,1]
	v_pk_fma_f32 v[238:239], v[182:183], v[246:247], v[238:239] op_sel_hi:[0,1,1]
	v_cvt_pk_f32_fp8_sdwa v[242:243], v24 src0_sel:WORD_1
	v_cvt_pk_f32_fp8_e32 v[244:245], v25
	v_cvt_pk_f32_fp8_sdwa v[246:247], v25 src0_sel:WORD_1
	v_pk_fma_f32 v[216:217], v[182:183], v[240:241], v[216:217] op_sel:[1,0,0] op_sel_hi:[1,1,1]
	v_cvt_pk_f32_fp8_e32 v[240:241], v26
	v_pk_fma_f32 v[226:227], v[182:183], v[242:243], v[226:227] op_sel:[1,0,0] op_sel_hi:[1,1,1]
	v_pk_fma_f32 v[228:229], v[182:183], v[244:245], v[228:229] op_sel:[1,0,0] op_sel_hi:[1,1,1]
	v_pk_fma_f32 v[230:231], v[182:183], v[246:247], v[230:231] op_sel:[1,0,0] op_sel_hi:[1,1,1]
	v_cvt_pk_f32_fp8_sdwa v[242:243], v26 src0_sel:WORD_1
	v_cvt_pk_f32_fp8_e32 v[244:245], v27
	v_cvt_pk_f32_fp8_sdwa v[246:247], v27 src0_sel:WORD_1
	v_pk_fma_f32 v[232:233], v[182:183], v[240:241], v[232:233] op_sel:[1,0,0] op_sel_hi:[1,1,1]
	s_waitcnt vmcnt(25)
	v_cvt_pk_f32_fp8_e32 v[240:241], v28
	v_pk_fma_f32 v[234:235], v[182:183], v[242:243], v[234:235] op_sel:[1,0,0] op_sel_hi:[1,1,1]
	v_pk_fma_f32 v[236:237], v[182:183], v[244:245], v[236:237] op_sel:[1,0,0] op_sel_hi:[1,1,1]
	v_pk_fma_f32 v[238:239], v[182:183], v[246:247], v[238:239] op_sel:[1,0,0] op_sel_hi:[1,1,1]
	v_cvt_pk_f32_fp8_sdwa v[242:243], v28 src0_sel:WORD_1
	v_cvt_pk_f32_fp8_e32 v[244:245], v29
	v_cvt_pk_f32_fp8_sdwa v[246:247], v29 src0_sel:WORD_1
	v_pk_fma_f32 v[216:217], v[184:185], v[240:241], v[216:217] op_sel_hi:[0,1,1]
	v_cvt_pk_f32_fp8_e32 v[240:241], v30
	v_pk_fma_f32 v[226:227], v[184:185], v[242:243], v[226:227] op_sel_hi:[0,1,1]
	v_pk_fma_f32 v[228:229], v[184:185], v[244:245], v[228:229] op_sel_hi:[0,1,1]
	v_pk_fma_f32 v[230:231], v[184:185], v[246:247], v[230:231] op_sel_hi:[0,1,1]
	v_cvt_pk_f32_fp8_sdwa v[242:243], v30 src0_sel:WORD_1
	v_cvt_pk_f32_fp8_e32 v[244:245], v31
	v_cvt_pk_f32_fp8_sdwa v[246:247], v31 src0_sel:WORD_1
	v_pk_fma_f32 v[232:233], v[184:185], v[240:241], v[232:233] op_sel_hi:[0,1,1]
	s_waitcnt vmcnt(24)
	v_cvt_pk_f32_fp8_e32 v[240:241], v32
	v_pk_fma_f32 v[234:235], v[184:185], v[242:243], v[234:235] op_sel_hi:[0,1,1]
	v_pk_fma_f32 v[236:237], v[184:185], v[244:245], v[236:237] op_sel_hi:[0,1,1]
	v_pk_fma_f32 v[238:239], v[184:185], v[246:247], v[238:239] op_sel_hi:[0,1,1]
	v_cvt_pk_f32_fp8_sdwa v[242:243], v32 src0_sel:WORD_1
	v_cvt_pk_f32_fp8_e32 v[244:245], v33
	v_cvt_pk_f32_fp8_sdwa v[246:247], v33 src0_sel:WORD_1
	v_pk_fma_f32 v[216:217], v[184:185], v[240:241], v[216:217] op_sel:[1,0,0] op_sel_hi:[1,1,1]
	v_cvt_pk_f32_fp8_e32 v[240:241], v34
	v_pk_fma_f32 v[226:227], v[184:185], v[242:243], v[226:227] op_sel:[1,0,0] op_sel_hi:[1,1,1]
	v_pk_fma_f32 v[228:229], v[184:185], v[244:245], v[228:229] op_sel:[1,0,0] op_sel_hi:[1,1,1]
	v_pk_fma_f32 v[230:231], v[184:185], v[246:247], v[230:231] op_sel:[1,0,0] op_sel_hi:[1,1,1]
	v_cvt_pk_f32_fp8_sdwa v[242:243], v34 src0_sel:WORD_1
	v_cvt_pk_f32_fp8_e32 v[244:245], v35
	v_cvt_pk_f32_fp8_sdwa v[246:247], v35 src0_sel:WORD_1
	v_pk_fma_f32 v[232:233], v[184:185], v[240:241], v[232:233] op_sel:[1,0,0] op_sel_hi:[1,1,1]
	s_waitcnt vmcnt(23)
; DI void up_math(const u32x4 (&W)[16], const u32 (&pj)[16], float* __restrict__ yrow, int lane) {
;     ...
; #pragma unroll
;   for (int j = 0; j < 16; ++j) {
;     const float h = __uint_as_float(pj[j] << 16);
;     const f2 hh = {h, h};
; #pragma unroll
;     for (int d = 0; d < 4; ++d) {
;       f2 lo = __builtin_amdgcn_cvt_pk_f32_fp8((int)W[j][d], false);
;       f2 hi = __builtin_amdgcn_cvt_pk_f32_fp8((int)W[j][d], true);
;       y[2 * d] = lo * hh + y[2 * d];
;       y[2 * d + 1] = hi * hh + y[2 * d + 1];
;     }
;   }
	v_cvt_pk_f32_fp8_e32 v[240:241], v36
	v_pk_fma_f32 v[234:235], v[184:185], v[242:243], v[234:235] op_sel:[1,0,0] op_sel_hi:[1,1,1]
	v_pk_fma_f32 v[236:237], v[184:185], v[244:245], v[236:237] op_sel:[1,0,0] op_sel_hi:[1,1,1]
	v_pk_fma_f32 v[238:239], v[184:185], v[246:247], v[238:239] op_sel:[1,0,0] op_sel_hi:[1,1,1]
	v_cvt_pk_f32_fp8_sdwa v[242:243], v36 src0_sel:WORD_1
	v_cvt_pk_f32_fp8_e32 v[244:245], v37
	v_cvt_pk_f32_fp8_sdwa v[246:247], v37 src0_sel:WORD_1
	v_pk_fma_f32 v[216:217], v[186:187], v[240:241], v[216:217] op_sel_hi:[0,1,1]
	v_cvt_pk_f32_fp8_e32 v[240:241], v38
	v_pk_fma_f32 v[226:227], v[186:187], v[242:243], v[226:227] op_sel_hi:[0,1,1]
	v_pk_fma_f32 v[228:229], v[186:187], v[244:245], v[228:229] op_sel_hi:[0,1,1]
	v_pk_fma_f32 v[230:231], v[186:187], v[246:247], v[230:231] op_sel_hi:[0,1,1]
	v_cvt_pk_f32_fp8_sdwa v[242:243], v38 src0_sel:WORD_1
	v_cvt_pk_f32_fp8_e32 v[244:245], v39
	v_cvt_pk_f32_fp8_sdwa v[246:247], v39 src0_sel:WORD_1
	v_pk_fma_f32 v[232:233], v[186:187], v[240:241], v[232:233] op_sel_hi:[0,1,1]
	s_waitcnt vmcnt(22)
	v_cvt_pk_f32_fp8_e32 v[240:241], v40
	v_pk_fma_f32 v[234:235], v[186:187], v[242:243], v[234:235] op_sel_hi:[0,1,1]
	v_pk_fma_f32 v[236:237], v[186:187], v[244:245], v[236:237] op_sel_hi:[0,1,1]
	v_pk_fma_f32 v[238:239], v[186:187], v[246:247], v[238:239] op_sel_hi:[0,1,1]
	v_cvt_pk_f32_fp8_sdwa v[242:243], v40 src0_sel:WORD_1
	v_cvt_pk_f32_fp8_e32 v[244:245], v41
	v_cvt_pk_f32_fp8_sdwa v[246:247], v41 src0_sel:WORD_1
	v_pk_fma_f32 v[216:217], v[186:187], v[240:241], v[216:217] op_sel:[1,0,0] op_sel_hi:[1,1,1]
	v_cvt_pk_f32_fp8_e32 v[240:241], v42
	v_pk_fma_f32 v[226:227], v[186:187], v[242:243], v[226:227] op_sel:[1,0,0] op_sel_hi:[1,1,1]
	v_pk_fma_f32 v[228:229], v[186:187], v[244:245], v[228:229] op_sel:[1,0,0] op_sel_hi:[1,1,1]
	v_pk_fma_f32 v[230:231], v[186:187], v[246:247], v[230:231] op_sel:[1,0,0] op_sel_hi:[1,1,1]
	v_cvt_pk_f32_fp8_sdwa v[242:243], v42 src0_sel:WORD_1
	v_cvt_pk_f32_fp8_e32 v[244:245], v43
	v_cvt_pk_f32_fp8_sdwa v[246:247], v43 src0_sel:WORD_1
	v_pk_fma_f32 v[232:233], v[186:187], v[240:241], v[232:233] op_sel:[1,0,0] op_sel_hi:[1,1,1]
	s_waitcnt vmcnt(21)
	v_cvt_pk_f32_fp8_e32 v[240:241], v44
	v_pk_fma_f32 v[234:235], v[186:187], v[242:243], v[234:235] op_sel:[1,0,0] op_sel_hi:[1,1,1]
	v_pk_fma_f32 v[236:237], v[186:187], v[244:245], v[236:237] op_sel:[1,0,0] op_sel_hi:[1,1,1]
	v_pk_fma_f32 v[238:239], v[186:187], v[246:247], v[238:239] op_sel:[1,0,0] op_sel_hi:[1,1,1]
	v_cvt_pk_f32_fp8_sdwa v[242:243], v44 src0_sel:WORD_1
	v_cvt_pk_f32_fp8_e32 v[244:245], v45
	v_cvt_pk_f32_fp8_sdwa v[246:247], v45 src0_sel:WORD_1
	v_pk_fma_f32 v[216:217], v[190:191], v[240:241], v[216:217] op_sel_hi:[0,1,1]
	v_cvt_pk_f32_fp8_e32 v[240:241], v46
	v_pk_fma_f32 v[226:227], v[190:191], v[242:243], v[226:227] op_sel_hi:[0,1,1]
	v_pk_fma_f32 v[228:229], v[190:191], v[244:245], v[228:229] op_sel_hi:[0,1,1]
	v_pk_fma_f32 v[230:231], v[190:191], v[246:247], v[230:231] op_sel_hi:[0,1,1]
	v_cvt_pk_f32_fp8_sdwa v[242:243], v46 src0_sel:WORD_1
	v_cvt_pk_f32_fp8_e32 v[244:245], v47
	v_cvt_pk_f32_fp8_sdwa v[246:247], v47 src0_sel:WORD_1
	v_pk_fma_f32 v[232:233], v[190:191], v[240:241], v[232:233] op_sel_hi:[0,1,1]
	s_waitcnt vmcnt(20)
	v_cvt_pk_f32_fp8_e32 v[240:241], v48
	v_pk_fma_f32 v[234:235], v[190:191], v[242:243], v[234:235] op_sel_hi:[0,1,1]
	v_pk_fma_f32 v[236:237], v[190:191], v[244:245], v[236:237] op_sel_hi:[0,1,1]
	v_pk_fma_f32 v[238:239], v[190:191], v[246:247], v[238:239] op_sel_hi:[0,1,1]
	v_cvt_pk_f32_fp8_sdwa v[242:243], v48 src0_sel:WORD_1
	v_cvt_pk_f32_fp8_e32 v[244:245], v49
	v_cvt_pk_f32_fp8_sdwa v[246:247], v49 src0_sel:WORD_1
	v_pk_fma_f32 v[216:217], v[190:191], v[240:241], v[216:217] op_sel:[1,0,0] op_sel_hi:[1,1,1]
	v_cvt_pk_f32_fp8_e32 v[240:241], v50
	v_pk_fma_f32 v[226:227], v[190:191], v[242:243], v[226:227] op_sel:[1,0,0] op_sel_hi:[1,1,1]
	v_pk_fma_f32 v[228:229], v[190:191], v[244:245], v[228:229] op_sel:[1,0,0] op_sel_hi:[1,1,1]
	v_pk_fma_f32 v[230:231], v[190:191], v[246:247], v[230:231] op_sel:[1,0,0] op_sel_hi:[1,1,1]
	v_cvt_pk_f32_fp8_sdwa v[242:243], v50 src0_sel:WORD_1
	v_cvt_pk_f32_fp8_e32 v[244:245], v51
	v_cvt_pk_f32_fp8_sdwa v[246:247], v51 src0_sel:WORD_1
	v_pk_fma_f32 v[232:233], v[190:191], v[240:241], v[232:233] op_sel:[1,0,0] op_sel_hi:[1,1,1]
	s_waitcnt vmcnt(19)
	v_cvt_pk_f32_fp8_e32 v[240:241], v52
	v_pk_fma_f32 v[234:235], v[190:191], v[242:243], v[234:235] op_sel:[1,0,0] op_sel_hi:[1,1,1]
	v_pk_fma_f32 v[236:237], v[190:191], v[244:245], v[236:237] op_sel:[1,0,0] op_sel_hi:[1,1,1]
	v_pk_fma_f32 v[238:239], v[190:191], v[246:247], v[238:239] op_sel:[1,0,0] op_sel_hi:[1,1,1]
	v_cvt_pk_f32_fp8_sdwa v[242:243], v52 src0_sel:WORD_1
	v_cvt_pk_f32_fp8_e32 v[244:245], v53
	v_cvt_pk_f32_fp8_sdwa v[246:247], v53 src0_sel:WORD_1
	v_pk_fma_f32 v[216:217], v[192:193], v[240:241], v[216:217] op_sel_hi:[0,1,1]
	v_cvt_pk_f32_fp8_e32 v[240:241], v54
	v_pk_fma_f32 v[226:227], v[192:193], v[242:243], v[226:227] op_sel_hi:[0,1,1]
	v_pk_fma_f32 v[228:229], v[192:193], v[244:245], v[228:229] op_sel_hi:[0,1,1]
	v_pk_fma_f32 v[230:231], v[192:193], v[246:247], v[230:231] op_sel_hi:[0,1,1]
	v_cvt_pk_f32_fp8_sdwa v[242:243], v54 src0_sel:WORD_1
	v_cvt_pk_f32_fp8_e32 v[244:245], v55
	v_cvt_pk_f32_fp8_sdwa v[246:247], v55 src0_sel:WORD_1
	v_pk_fma_f32 v[232:233], v[192:193], v[240:241], v[232:233] op_sel_hi:[0,1,1]
	s_waitcnt vmcnt(18)
; DI void up_math(const u32x4 (&W)[16], const u32 (&pj)[16], float* __restrict__ yrow, int lane) {
;     ...
;   const bool b5 = lane & 32, b4 = lane & 16, b3 = lane & 8;
;   f2 q4[4];
; #pragma unroll
;   for (int i = 0; i < 4; ++i) {
;     f2 snd = b5 ? y[i] : y[i + 4]; f2 kp = b5 ? y[i + 4] : y[i];
;     q4[i] = f2{kp.x + __shfl_xor(snd.x, 32), kp.y + __shfl_xor(snd.y, 32)};
;   }
;   f2 r2[2];
; #pragma unroll
;   for (int i = 0; i < 2; ++i) {
;     f2 snd = b4 ? q4[i] : q4[i + 2]; f2 kp = b4 ? q4[i + 2] : q4[i];
;     r2[i] = f2{kp.x + __shfl_xor(snd.x, 16), kp.y + __shfl_xor(snd.y, 16)};
;   }
;   f2 a;
;   { f2 snd = b3 ? r2[0] : r2[1]; f2 kp = b3 ? r2[1] : r2[0]; a = f2{kp.x + __shfl_xor(snd.x, 8), kp.y + __shfl_xor(snd.y, 8)}; }
;   const int ci = (b5 ? 4 : 0) + (b4 ? 2 : 0) + (b3 ? 1 : 0);
;   *(float2*)(yrow + (lane & 7) * 16 + 2 * ci) = make_float2(a.x, a.y);
; DI void peer_up_phase(const Params& p, unsigned char* smem, int layer, u32* ctr) {
;     ...
;         __builtin_amdgcn_sched_barrier(0);
;         if (tl + 2 < 16) up_issue(WA, pA, pl + (tl + 2) * 128, wbase, grp);
	v_cvt_pk_f32_fp8_e32 v[240:241], v56
	v_pk_fma_f32 v[234:235], v[192:193], v[242:243], v[234:235] op_sel_hi:[0,1,1]
	v_pk_fma_f32 v[236:237], v[192:193], v[244:245], v[236:237] op_sel_hi:[0,1,1]
	v_pk_fma_f32 v[238:239], v[192:193], v[246:247], v[238:239] op_sel_hi:[0,1,1]
	v_cvt_pk_f32_fp8_sdwa v[242:243], v56 src0_sel:WORD_1
	v_cvt_pk_f32_fp8_e32 v[244:245], v57
	v_cvt_pk_f32_fp8_sdwa v[246:247], v57 src0_sel:WORD_1
	v_pk_fma_f32 v[216:217], v[192:193], v[240:241], v[216:217] op_sel:[1,0,0] op_sel_hi:[1,1,1]
	v_cvt_pk_f32_fp8_e32 v[240:241], v58
	v_pk_fma_f32 v[226:227], v[192:193], v[242:243], v[226:227] op_sel:[1,0,0] op_sel_hi:[1,1,1]
	v_pk_fma_f32 v[228:229], v[192:193], v[244:245], v[228:229] op_sel:[1,0,0] op_sel_hi:[1,1,1]
	v_pk_fma_f32 v[230:231], v[192:193], v[246:247], v[230:231] op_sel:[1,0,0] op_sel_hi:[1,1,1]
	v_cvt_pk_f32_fp8_sdwa v[242:243], v58 src0_sel:WORD_1
	v_cvt_pk_f32_fp8_e32 v[244:245], v59
	v_cvt_pk_f32_fp8_sdwa v[246:247], v59 src0_sel:WORD_1
	v_pk_fma_f32 v[232:233], v[192:193], v[240:241], v[232:233] op_sel:[1,0,0] op_sel_hi:[1,1,1]
	s_waitcnt vmcnt(17)
	v_cvt_pk_f32_fp8_e32 v[240:241], v60
	v_pk_fma_f32 v[234:235], v[192:193], v[242:243], v[234:235] op_sel:[1,0,0] op_sel_hi:[1,1,1]
	v_pk_fma_f32 v[236:237], v[192:193], v[244:245], v[236:237] op_sel:[1,0,0] op_sel_hi:[1,1,1]
	v_pk_fma_f32 v[238:239], v[192:193], v[246:247], v[238:239] op_sel:[1,0,0] op_sel_hi:[1,1,1]
	v_cvt_pk_f32_fp8_sdwa v[242:243], v60 src0_sel:WORD_1
	v_cvt_pk_f32_fp8_e32 v[244:245], v61
	v_cvt_pk_f32_fp8_sdwa v[246:247], v61 src0_sel:WORD_1
	v_pk_fma_f32 v[216:217], v[194:195], v[240:241], v[216:217] op_sel_hi:[0,1,1]
	v_cvt_pk_f32_fp8_e32 v[240:241], v62
	v_pk_fma_f32 v[226:227], v[194:195], v[242:243], v[226:227] op_sel_hi:[0,1,1]
	v_pk_fma_f32 v[228:229], v[194:195], v[244:245], v[228:229] op_sel_hi:[0,1,1]
	v_pk_fma_f32 v[230:231], v[194:195], v[246:247], v[230:231] op_sel_hi:[0,1,1]
	v_cvt_pk_f32_fp8_sdwa v[242:243], v62 src0_sel:WORD_1
	v_cvt_pk_f32_fp8_e32 v[244:245], v63
	v_cvt_pk_f32_fp8_sdwa v[246:247], v63 src0_sel:WORD_1
	v_pk_fma_f32 v[232:233], v[194:195], v[240:241], v[232:233] op_sel_hi:[0,1,1]
	s_waitcnt vmcnt(16)
	v_cvt_pk_f32_fp8_e32 v[240:241], v64
	v_pk_fma_f32 v[234:235], v[194:195], v[242:243], v[234:235] op_sel_hi:[0,1,1]
	v_pk_fma_f32 v[236:237], v[194:195], v[244:245], v[236:237] op_sel_hi:[0,1,1]
	v_pk_fma_f32 v[238:239], v[194:195], v[246:247], v[238:239] op_sel_hi:[0,1,1]
	v_cvt_pk_f32_fp8_sdwa v[242:243], v64 src0_sel:WORD_1
	v_cvt_pk_f32_fp8_e32 v[244:245], v65
	v_cvt_pk_f32_fp8_sdwa v[246:247], v65 src0_sel:WORD_1
	v_pk_fma_f32 v[216:217], v[194:195], v[240:241], v[216:217] op_sel:[1,0,0] op_sel_hi:[1,1,1]
	v_cvt_pk_f32_fp8_e32 v[240:241], v66
	v_pk_fma_f32 v[226:227], v[194:195], v[242:243], v[226:227] op_sel:[1,0,0] op_sel_hi:[1,1,1]
	v_pk_fma_f32 v[228:229], v[194:195], v[244:245], v[228:229] op_sel:[1,0,0] op_sel_hi:[1,1,1]
	v_pk_fma_f32 v[230:231], v[194:195], v[246:247], v[230:231] op_sel:[1,0,0] op_sel_hi:[1,1,1]
	v_cvt_pk_f32_fp8_sdwa v[242:243], v66 src0_sel:WORD_1
	v_cvt_pk_f32_fp8_e32 v[244:245], v67
	v_cvt_pk_f32_fp8_sdwa v[246:247], v67 src0_sel:WORD_1
	v_pk_fma_f32 v[232:233], v[194:195], v[240:241], v[232:233] op_sel:[1,0,0] op_sel_hi:[1,1,1]
	v_pk_fma_f32 v[234:235], v[194:195], v[242:243], v[234:235] op_sel:[1,0,0] op_sel_hi:[1,1,1]
	v_pk_fma_f32 v[236:237], v[194:195], v[244:245], v[236:237] op_sel:[1,0,0] op_sel_hi:[1,1,1]
	v_pk_fma_f32 v[238:239], v[194:195], v[246:247], v[238:239] op_sel:[1,0,0] op_sel_hi:[1,1,1]
	s_nop 1
	v_permlane32_swap_b32_e32 v216, v232
	v_permlane32_swap_b32_e32 v217, v233
	v_permlane32_swap_b32_e32 v228, v236
	v_permlane32_swap_b32_e32 v229, v237
	v_permlane32_swap_b32_e32 v226, v234
	v_permlane32_swap_b32_e32 v227, v235
	v_permlane32_swap_b32_e32 v230, v238
	v_permlane32_swap_b32_e32 v231, v239
	v_pk_add_f32 v[216:217], v[216:217], v[232:233]
	v_pk_add_f32 v[228:229], v[228:229], v[236:237]
	v_pk_add_f32 v[226:227], v[226:227], v[234:235]
	v_pk_add_f32 v[230:231], v[230:231], v[238:239]
	s_nop 1
	v_permlane16_swap_b32_e32 v216, v228
	v_permlane16_swap_b32_e32 v217, v229
	v_permlane16_swap_b32_e32 v226, v230
	v_permlane16_swap_b32_e32 v227, v231
	v_pk_add_f32 v[216:217], v[216:217], v[228:229]
	v_pk_add_f32 v[226:227], v[226:227], v[230:231]
	s_nop 0
	v_cndmask_b32_e64 v132, v217, v227, s[10:11]
	v_cndmask_b32_e64 v147, v216, v226, s[10:11]
	ds_bpermute_b32 v228, v143, v147
	ds_bpermute_b32 v229, v143, v132
	v_cndmask_b32_e64 v217, v227, v217, s[10:11]
	v_cndmask_b32_e64 v216, v226, v216, s[10:11]
	s_waitcnt lgkmcnt(0)
	v_pk_add_f32 v[216:217], v[216:217], v[228:229]
	global_store_dwordx2 v[188:189], v[216:217], off
	s_cmp_gt_u32 s36, 13
	s_cselect_b64 s[28:29], -1, 0
	s_cbranch_scc1 .LBB0_1649
; DI void up_issue(u32x4 (&W)[16], u32 (&pj)[16], const u32* pl, const unsigned char* wbase, int grp) {
; #pragma unroll
;   for (int j = 0; j < 16; ++j) {
;     pj[j] = pl[8 * j + grp];
;     W[j] = *(const u32x4*)(wbase + (size_t)(pj[j] >> 16) * 1024);
;   }
; }
; DI void peer_up_phase(const Params& p, unsigned char* smem, int layer, u32* ctr) {
;     ...
;         if (tl + 2 < 16) up_issue(WA, pA, pl + (tl + 2) * 128, wbase, grp);
	ds_read_u16_d16_hi v178, v145 offset:512
	ds_read_u16_d16_hi v179, v145 offset:544
	ds_read_u16_d16_hi v180, v145 offset:576
	ds_read_u16_d16_hi v181, v145 offset:608
	ds_read_u16_d16_hi v182, v145 offset:640
	ds_read_u16_d16_hi v183, v145 offset:672
	ds_read_u16_d16_hi v184, v145 offset:704
	ds_read_u16_d16_hi v185, v145 offset:736
	ds_read_u16_d16_hi v186, v145 offset:768
	ds_read_u16_d16_hi v187, v145 offset:800
	ds_read_u16_d16_hi v190, v145 offset:832
	ds_read_u16_d16_hi v191, v145 offset:864
	ds_read_u16_d16_hi v192, v145 offset:896
	ds_read_u16_d16_hi v193, v145 offset:928
	ds_read_u16_d16_hi v194, v145 offset:960
	ds_read_u16_d16_hi v195, v145 offset:992
	ds_read_u16 v4, v145 offset:514
	ds_read_u16 v8, v145 offset:546
	ds_read_u16 v12, v145 offset:578
	ds_read_u16 v16, v145 offset:610
	ds_read_u16 v20, v145 offset:642
	ds_read_u16 v24, v145 offset:674
	ds_read_u16 v28, v145 offset:706
	ds_read_u16 v32, v145 offset:738
	ds_read_u16 v36, v145 offset:770
	ds_read_u16 v40, v145 offset:802
	ds_read_u16 v44, v145 offset:834
	ds_read_u16 v48, v145 offset:866
	ds_read_u16 v52, v145 offset:898
	ds_read_u16 v56, v145 offset:930
	ds_read_u16 v60, v145 offset:962
	ds_read_u16 v64, v145 offset:994
	s_waitcnt lgkmcnt(15)
	v_lshl_add_u32 v4, v4, 10, v250
	global_load_dwordx4 v[4:7], v4, s[98:99]
	s_waitcnt lgkmcnt(14)
	v_lshl_add_u32 v8, v8, 10, v250
	global_load_dwordx4 v[8:11], v8, s[98:99]
	s_waitcnt lgkmcnt(13)
	v_lshl_add_u32 v12, v12, 10, v250
	global_load_dwordx4 v[12:15], v12, s[98:99]
	s_waitcnt lgkmcnt(12)
	v_lshl_add_u32 v16, v16, 10, v250
	global_load_dwordx4 v[16:19], v16, s[98:99]
	s_waitcnt lgkmcnt(11)
	v_lshl_add_u32 v20, v20, 10, v250
	global_load_dwordx4 v[20:23], v20, s[98:99]
	s_waitcnt lgkmcnt(10)
	v_lshl_add_u32 v24, v24, 10, v250
	global_load_dwordx4 v[24:27], v24, s[98:99]
	s_waitcnt lgkmcnt(9)
	v_lshl_add_u32 v28, v28, 10, v250
	global_load_dwordx4 v[28:31], v28, s[98:99]
	s_waitcnt lgkmcnt(8)
	v_lshl_add_u32 v32, v32, 10, v250
	global_load_dwordx4 v[32:35], v32, s[98:99]
	s_waitcnt lgkmcnt(7)
	v_lshl_add_u32 v36, v36, 10, v250
	global_load_dwordx4 v[36:39], v36, s[98:99]
	s_waitcnt lgkmcnt(6)
	v_lshl_add_u32 v40, v40, 10, v250
	global_load_dwordx4 v[40:43], v40, s[98:99]
	s_waitcnt lgkmcnt(5)
	v_lshl_add_u32 v44, v44, 10, v250
	global_load_dwordx4 v[44:47], v44, s[98:99]
	s_waitcnt lgkmcnt(4)
	v_lshl_add_u32 v48, v48, 10, v250
	global_load_dwordx4 v[48:51], v48, s[98:99]
	s_waitcnt lgkmcnt(3)
	v_lshl_add_u32 v52, v52, 10, v250
	global_load_dwordx4 v[52:55], v52, s[98:99]
	s_waitcnt lgkmcnt(2)
	v_lshl_add_u32 v56, v56, 10, v250
	global_load_dwordx4 v[56:59], v56, s[98:99]
	s_waitcnt lgkmcnt(1)
	v_lshl_add_u32 v60, v60, 10, v250
	global_load_dwordx4 v[60:63], v60, s[98:99]
	s_waitcnt lgkmcnt(0)
	v_lshl_add_u32 v64, v64, 10, v250
	global_load_dwordx4 v[64:67], v64, s[98:99]
	s_branch .LBB0_1649
